# GEMM MFMA phases: A-major ordering inside each 8-MFMA group (consecutive MFMAs share the A fragment instead of the B fragment)
# baseline (speedup 1.0000x reference)
; #define PG8_STAGE(bufoff, gbase, voff) do { _Pragma("unroll") for (int _i = 0; _i < 2; ++_i) \
;         __builtin_amdgcn_global_load_lds((const unsigned*)((const char*)(gbase) + (voff)[_i]), (LAS unsigned*)(lds + (bufoff) + ldsw + _i * 8192), 16, 0, 0); } while (0)
; #define PG8_LDA(dst, b, h) do { _Pragma("unroll") for (int m = 0; m < 4; ++m) _Pragma("unroll") for (int k = 0; k < 2; ++k) dst[m][k] = *(const LAS bf16x8*)(lds + PG8_SA(b, h) + aoff + m * 2048 + k * 1024); } while (0)
; #define PG8_LDB(dst, b, h) do { _Pragma("unroll") for (int n = 0; n < 2; ++n) _Pragma("unroll") for (int k = 0; k < 2; ++k) dst[n][k] = *(const LAS bf16x8*)(lds + PG8_SB(b, h) + boff + n * 2048 + k * 1024); } while (0)
; #define PG8_MMA(ai, bj, At, Bt) do { __builtin_amdgcn_s_setprio(1); _Pragma("unroll") for (int m = 0; m < 4; ++m) _Pragma("unroll") for (int n = 0; n < 2; ++n) _Pragma("unroll") for (int k = 0; k < 2; ++k) \
;         acc[ai][bj][m][n] = __builtin_amdgcn_mfma_f32_16x16x32_bf16(Bt[n][k], At[m][k], acc[ai][bj][m][n], 0, 0, 0); __builtin_amdgcn_s_setprio(0); } while (0)
; #define PG8_WAIT_V(n) asm volatile("s_waitcnt vmcnt(" #n ")" ::: "memory")
; #define PG8_WAIT_L(n) asm volatile("s_waitcnt lgkmcnt(" #n ")" ::: "memory")
; #define PG8_BAR __builtin_amdgcn_s_barrier()
; #define PG8_SCHED __builtin_amdgcn_sched_barrier(0)
; template <class Epi>
; __device__ __forceinline__ void gemm_phase(LAS unsigned char* lds, const Gemm g, const StaticOrder& S, const Epi& E) {
;     ...
;             PG8_LDB(B0, 0, 0); PG8_LDB(B1, 0, 1); PG8_SCHED; PG8_LDA(At, 0, 0); PG8_STAGE(PG8_SA(1, 1), a1 + hA, voffA);
;             PG8_WAIT_V(8); PG8_WAIT_L(0); PG8_BAR; PG8_MMA(0, 0, At, B0); PG8_MMA(0, 1, At, B1); PG8_BAR; PG8_SCHED;
.LBB0_132:
	s_add_u32 s34, s8, 0xfffc0080
	s_addc_u32 s35, s9, -1
	s_add_i32 s42, 0, 0x10000
	s_cmp_eq_u32 s41, 12
	s_cselect_b32 s37, s7, s35
	s_cselect_b32 s36, s27, s34
	v_add_u32_e32 v153, s42, v139
	s_cselect_b32 s35, s25, s40
	s_cselect_b32 s34, s38, s39
	s_add_i32 s44, 0, 0x14000
	ds_read_b128 v[166:169], v153
	ds_read_b128 v[170:173], v153 offset:1024
	ds_read_b128 v[174:177], v153 offset:2048
	ds_read_b128 v[182:185], v153 offset:3072
	v_add_u32_e32 v153, s44, v139
	ds_read_b128 v[186:189], v153
	ds_read_b128 v[190:193], v153 offset:1024
	ds_read_b128 v[194:197], v153 offset:2048
	ds_read_b128 v[198:201], v153 offset:3072
	v_lshl_add_u64 v[178:179], s[8:9], 0, v[162:163]
	s_add_i32 m0, s19, 0xc000
	ds_read_b128 v[202:205], v149
	ds_read_b128 v[206:209], v149 offset:1024
	ds_read_b128 v[210:213], v149 offset:2048
	ds_read_b128 v[214:217], v149 offset:3072
	ds_read_b128 v[218:221], v149 offset:4096
	ds_read_b128 v[232:235], v149 offset:5120
	ds_read_b128 v[236:239], v149 offset:6144
	ds_read_b128 v[240:243], v149 offset:7168
	global_load_lds_dwordx4 v[178:179], off
	v_lshl_add_u64 v[178:179], s[8:9], 0, v[164:165]
	s_add_i32 m0, s19, 0xe000
	s_nop 0
	global_load_lds_dwordx4 v[178:179], off
	s_waitcnt vmcnt(8)
	s_waitcnt lgkmcnt(0)
	s_barrier
	s_setprio 1
	v_mfma_f32_16x16x32_bf16 v[126:129], v[166:169], v[202:205], v[126:129]
	v_mfma_f32_16x16x32_bf16 v[110:113], v[166:169], v[210:213], v[110:113]
	v_mfma_f32_16x16x32_bf16 v[94:97], v[166:169], v[218:221], v[94:97]
	v_mfma_f32_16x16x32_bf16 v[78:81], v[166:169], v[236:239], v[78:81]
	v_mfma_f32_16x16x32_bf16 v[122:125], v[174:177], v[202:205], v[122:125]
	v_mfma_f32_16x16x32_bf16 v[106:109], v[174:177], v[210:213], v[106:109]
	v_mfma_f32_16x16x32_bf16 v[90:93], v[174:177], v[218:221], v[90:93]
	v_mfma_f32_16x16x32_bf16 v[74:77], v[174:177], v[236:239], v[74:77]
	v_mfma_f32_16x16x32_bf16 v[126:129], v[170:173], v[206:209], v[126:129]
	v_mfma_f32_16x16x32_bf16 v[110:113], v[170:173], v[214:217], v[110:113]
	v_mfma_f32_16x16x32_bf16 v[94:97], v[170:173], v[232:235], v[94:97]
	v_mfma_f32_16x16x32_bf16 v[78:81], v[170:173], v[240:243], v[78:81]
	v_mfma_f32_16x16x32_bf16 v[122:125], v[182:185], v[206:209], v[122:125]
	v_mfma_f32_16x16x32_bf16 v[106:109], v[182:185], v[214:217], v[106:109]
	v_mfma_f32_16x16x32_bf16 v[90:93], v[182:185], v[232:235], v[90:93]
	v_mfma_f32_16x16x32_bf16 v[74:77], v[182:185], v[240:243], v[74:77]
	v_mfma_f32_16x16x32_bf16 v[118:121], v[186:189], v[202:205], v[118:121]
	v_mfma_f32_16x16x32_bf16 v[102:105], v[186:189], v[210:213], v[102:105]
	v_mfma_f32_16x16x32_bf16 v[86:89], v[186:189], v[218:221], v[86:89]
	v_mfma_f32_16x16x32_bf16 v[70:73], v[186:189], v[236:239], v[70:73]
	v_mfma_f32_16x16x32_bf16 v[114:117], v[194:197], v[202:205], v[114:117]
	v_mfma_f32_16x16x32_bf16 v[98:101], v[194:197], v[210:213], v[98:101]
	v_mfma_f32_16x16x32_bf16 v[82:85], v[194:197], v[218:221], v[82:85]
	v_mfma_f32_16x16x32_bf16 v[66:69], v[194:197], v[236:239], v[66:69]
	v_mfma_f32_16x16x32_bf16 v[118:121], v[190:193], v[206:209], v[118:121]
	v_mfma_f32_16x16x32_bf16 v[102:105], v[190:193], v[214:217], v[102:105]
	v_mfma_f32_16x16x32_bf16 v[86:89], v[190:193], v[232:235], v[86:89]
	v_mfma_f32_16x16x32_bf16 v[70:73], v[190:193], v[240:243], v[70:73]
	v_mfma_f32_16x16x32_bf16 v[114:117], v[198:201], v[206:209], v[114:117]
	v_mfma_f32_16x16x32_bf16 v[98:101], v[198:201], v[214:217], v[98:101]
	v_mfma_f32_16x16x32_bf16 v[82:85], v[198:201], v[232:235], v[82:85]
	v_mfma_f32_16x16x32_bf16 v[66:69], v[198:201], v[240:243], v[66:69]
	s_setprio 0
	s_barrier
	s_add_i32 s42, s42, s51
	v_lshl_add_u64 v[178:179], s[34:35], 0, v[132:133]
	s_mov_b32 m0, s42
	ds_read_b128 v[202:205], v149 offset:16384
	ds_read_b128 v[206:209], v149 offset:17408
	ds_read_b128 v[210:213], v149 offset:18432
	ds_read_b128 v[214:217], v149 offset:19456
	ds_read_b128 v[218:221], v149 offset:20480
	ds_read_b128 v[232:235], v149 offset:21504
	ds_read_b128 v[236:239], v149 offset:22528
	ds_read_b128 v[240:243], v149 offset:23552
	global_load_lds_dwordx4 v[178:179], off
	s_add_i32 m0, s42, 0x2000
	s_add_u32 s42, s34, 0x40000
	v_lshl_add_u64 v[244:245], s[34:35], 0, v[136:137]
	s_addc_u32 s43, s35, 0
	s_add_i32 s44, s44, s51
	global_load_lds_dwordx4 v[244:245], off
	v_lshl_add_u64 v[246:247], s[42:43], 0, v[132:133]
	s_mov_b32 m0, s44
	v_lshl_add_u64 v[248:249], s[36:37], 0, v[134:135]
	global_load_lds_dwordx4 v[246:247], off
	v_lshl_add_u64 v[246:247], s[42:43], 0, v[136:137]
	s_add_i32 m0, s44, 0x2000
	s_nop 0
	global_load_lds_dwordx4 v[246:247], off
	v_lshl_add_u64 v[246:247], s[36:37], 0, v[130:131]
	s_mov_b32 m0, s19
	s_nop 0
	global_load_lds_dwordx4 v[246:247], off
	s_mov_b32 m0, s56
	s_nop 0
	global_load_lds_dwordx4 v[248:249], off
	s_waitcnt vmcnt(8)
	s_waitcnt lgkmcnt(0)
	s_barrier
; #define PG8_STAGE(bufoff, gbase, voff) do { _Pragma("unroll") for (int _i = 0; _i < 2; ++_i) \
;         __builtin_amdgcn_global_load_lds((const unsigned*)((const char*)(gbase) + (voff)[_i]), (LAS unsigned*)(lds + (bufoff) + ldsw + _i * 8192), 16, 0, 0); } while (0)
; #define PG8_LDA(dst, b, h) do { _Pragma("unroll") for (int m = 0; m < 4; ++m) _Pragma("unroll") for (int k = 0; k < 2; ++k) dst[m][k] = *(const LAS bf16x8*)(lds + PG8_SA(b, h) + aoff + m * 2048 + k * 1024); } while (0)
; #define PG8_LDB(dst, b, h) do { _Pragma("unroll") for (int n = 0; n < 2; ++n) _Pragma("unroll") for (int k = 0; k < 2; ++k) dst[n][k] = *(const LAS bf16x8*)(lds + PG8_SB(b, h) + boff + n * 2048 + k * 1024); } while (0)
; #define PG8_MMA(ai, bj, At, Bt) do { __builtin_amdgcn_s_setprio(1); _Pragma("unroll") for (int m = 0; m < 4; ++m) _Pragma("unroll") for (int n = 0; n < 2; ++n) _Pragma("unroll") for (int k = 0; k < 2; ++k) \
;         acc[ai][bj][m][n] = __builtin_amdgcn_mfma_f32_16x16x32_bf16(Bt[n][k], At[m][k], acc[ai][bj][m][n], 0, 0, 0); __builtin_amdgcn_s_setprio(0); } while (0)
; #define PG8_WAIT_V(n) asm volatile("s_waitcnt vmcnt(" #n ")" ::: "memory")
; #define PG8_WAIT_L(n) asm volatile("s_waitcnt lgkmcnt(" #n ")" ::: "memory")
; #define PG8_BAR __builtin_amdgcn_s_barrier()
; #define PG8_SCHED __builtin_amdgcn_sched_barrier(0)
; template <class Epi>
; __device__ __forceinline__ void gemm_phase(LAS unsigned char* lds, const Gemm g, const StaticOrder& S, const Epi& E) {
;     ...
;             PG8_WAIT_V(8); PG8_WAIT_L(0); PG8_BAR; PG8_MMA(1, 0, At, B0); PG8_MMA(1, 1, At, B1); PG8_BAR; PG8_SCHED;
;             PG8_LDB(B0, 1, 0); PG8_LDB(B1, 1, 1); PG8_SCHED; PG8_LDA(At, 1, 0); PG8_STAGE(PG8_SA(0, 1), a2 + hA, voffA);
;             PG8_WAIT_V(8); PG8_WAIT_L(0); PG8_BAR; PG8_MMA(0, 0, At, B0); PG8_MMA(0, 1, At, B1); PG8_BAR; PG8_SCHED;
	s_setprio 1
	v_mfma_f32_16x16x32_bf16 v[62:65], v[166:169], v[202:205], v[62:65]
	v_mfma_f32_16x16x32_bf16 v[46:49], v[166:169], v[210:213], v[46:49]
	v_mfma_f32_16x16x32_bf16 v[30:33], v[166:169], v[218:221], v[30:33]
	v_mfma_f32_16x16x32_bf16 v[14:17], v[166:169], v[236:239], v[14:17]
	v_mfma_f32_16x16x32_bf16 v[58:61], v[174:177], v[202:205], v[58:61]
	v_mfma_f32_16x16x32_bf16 v[42:45], v[174:177], v[210:213], v[42:45]
	v_mfma_f32_16x16x32_bf16 v[26:29], v[174:177], v[218:221], v[26:29]
	v_mfma_f32_16x16x32_bf16 v[10:13], v[174:177], v[236:239], v[10:13]
	v_mfma_f32_16x16x32_bf16 v[62:65], v[170:173], v[206:209], v[62:65]
	v_mfma_f32_16x16x32_bf16 v[46:49], v[170:173], v[214:217], v[46:49]
	v_mfma_f32_16x16x32_bf16 v[30:33], v[170:173], v[232:235], v[30:33]
	v_mfma_f32_16x16x32_bf16 v[14:17], v[170:173], v[240:243], v[14:17]
	v_mfma_f32_16x16x32_bf16 v[58:61], v[182:185], v[206:209], v[58:61]
	v_mfma_f32_16x16x32_bf16 v[42:45], v[182:185], v[214:217], v[42:45]
	v_mfma_f32_16x16x32_bf16 v[26:29], v[182:185], v[232:235], v[26:29]
	v_mfma_f32_16x16x32_bf16 v[10:13], v[182:185], v[240:243], v[10:13]
	v_mfma_f32_16x16x32_bf16 v[54:57], v[186:189], v[202:205], v[54:57]
	v_mfma_f32_16x16x32_bf16 v[38:41], v[186:189], v[210:213], v[38:41]
	v_mfma_f32_16x16x32_bf16 v[22:25], v[186:189], v[218:221], v[22:25]
	v_mfma_f32_16x16x32_bf16 v[6:9], v[186:189], v[236:239], v[6:9]
	v_mfma_f32_16x16x32_bf16 v[50:53], v[194:197], v[202:205], v[50:53]
	v_mfma_f32_16x16x32_bf16 v[34:37], v[194:197], v[210:213], v[34:37]
	v_mfma_f32_16x16x32_bf16 v[18:21], v[194:197], v[218:221], v[18:21]
	v_mfma_f32_16x16x32_bf16 v[2:5], v[194:197], v[236:239], v[2:5]
	v_mfma_f32_16x16x32_bf16 v[54:57], v[190:193], v[206:209], v[54:57]
	v_mfma_f32_16x16x32_bf16 v[38:41], v[190:193], v[214:217], v[38:41]
	v_mfma_f32_16x16x32_bf16 v[22:25], v[190:193], v[232:235], v[22:25]
	v_mfma_f32_16x16x32_bf16 v[6:9], v[190:193], v[240:243], v[6:9]
	v_mfma_f32_16x16x32_bf16 v[50:53], v[198:201], v[206:209], v[50:53]
	v_mfma_f32_16x16x32_bf16 v[34:37], v[198:201], v[214:217], v[34:37]
	v_mfma_f32_16x16x32_bf16 v[18:21], v[198:201], v[232:235], v[18:21]
	v_mfma_f32_16x16x32_bf16 v[2:5], v[198:201], v[240:243], v[2:5]
	s_setprio 0
	s_barrier
	s_add_i32 s42, 0, 0x18000
	v_add_u32_e32 v153, s42, v139
	s_add_i32 s43, 0, 0x1c000
	ds_read_b128 v[166:169], v153
	ds_read_b128 v[170:173], v153 offset:1024
	ds_read_b128 v[174:177], v153 offset:2048
	ds_read_b128 v[182:185], v153 offset:3072
	v_add_u32_e32 v153, s43, v139
	ds_read_b128 v[186:189], v153
	ds_read_b128 v[190:193], v153 offset:1024
	ds_read_b128 v[194:197], v153 offset:2048
	ds_read_b128 v[198:201], v153 offset:3072
	s_add_u32 s36, s36, 0x40000
	s_addc_u32 s37, s37, 0
	s_mov_b32 m0, s57
	v_lshl_add_u64 v[250:251], s[36:37], 0, v[130:131]
	ds_read_b128 v[202:205], v149 offset:32768
	ds_read_b128 v[206:209], v149 offset:33792
	ds_read_b128 v[210:213], v149 offset:34816
	ds_read_b128 v[214:217], v149 offset:35840
	ds_read_b128 v[218:221], v149 offset:36864
	ds_read_b128 v[232:235], v149 offset:37888
	ds_read_b128 v[236:239], v149 offset:38912
	ds_read_b128 v[240:243], v149 offset:39936
	global_load_lds_dwordx4 v[250:251], off
	v_lshl_add_u64 v[250:251], s[36:37], 0, v[134:135]
	s_mov_b32 m0, s58
	s_nop 0
	global_load_lds_dwordx4 v[250:251], off
	s_waitcnt vmcnt(8)
	s_waitcnt lgkmcnt(0)
	s_barrier
	s_setprio 1
	v_mfma_f32_16x16x32_bf16 v[126:129], v[166:169], v[202:205], v[126:129]
	v_mfma_f32_16x16x32_bf16 v[110:113], v[166:169], v[210:213], v[110:113]
	v_mfma_f32_16x16x32_bf16 v[94:97], v[166:169], v[218:221], v[94:97]
	v_mfma_f32_16x16x32_bf16 v[78:81], v[166:169], v[236:239], v[78:81]
	v_mfma_f32_16x16x32_bf16 v[122:125], v[174:177], v[202:205], v[122:125]
	v_mfma_f32_16x16x32_bf16 v[106:109], v[174:177], v[210:213], v[106:109]
	v_mfma_f32_16x16x32_bf16 v[90:93], v[174:177], v[218:221], v[90:93]
	v_mfma_f32_16x16x32_bf16 v[74:77], v[174:177], v[236:239], v[74:77]
	v_mfma_f32_16x16x32_bf16 v[126:129], v[170:173], v[206:209], v[126:129]
	v_mfma_f32_16x16x32_bf16 v[110:113], v[170:173], v[214:217], v[110:113]
	v_mfma_f32_16x16x32_bf16 v[94:97], v[170:173], v[232:235], v[94:97]
	v_mfma_f32_16x16x32_bf16 v[78:81], v[170:173], v[240:243], v[78:81]
	v_mfma_f32_16x16x32_bf16 v[122:125], v[182:185], v[206:209], v[122:125]
	v_mfma_f32_16x16x32_bf16 v[106:109], v[182:185], v[214:217], v[106:109]
	v_mfma_f32_16x16x32_bf16 v[90:93], v[182:185], v[232:235], v[90:93]
	v_mfma_f32_16x16x32_bf16 v[74:77], v[182:185], v[240:243], v[74:77]
	v_mfma_f32_16x16x32_bf16 v[118:121], v[186:189], v[202:205], v[118:121]
	v_mfma_f32_16x16x32_bf16 v[102:105], v[186:189], v[210:213], v[102:105]
	v_mfma_f32_16x16x32_bf16 v[86:89], v[186:189], v[218:221], v[86:89]
	v_mfma_f32_16x16x32_bf16 v[70:73], v[186:189], v[236:239], v[70:73]
	v_mfma_f32_16x16x32_bf16 v[114:117], v[194:197], v[202:205], v[114:117]
	v_mfma_f32_16x16x32_bf16 v[98:101], v[194:197], v[210:213], v[98:101]
	v_mfma_f32_16x16x32_bf16 v[82:85], v[194:197], v[218:221], v[82:85]
	v_mfma_f32_16x16x32_bf16 v[66:69], v[194:197], v[236:239], v[66:69]
	v_mfma_f32_16x16x32_bf16 v[118:121], v[190:193], v[206:209], v[118:121]
	v_mfma_f32_16x16x32_bf16 v[102:105], v[190:193], v[214:217], v[102:105]
	v_mfma_f32_16x16x32_bf16 v[86:89], v[190:193], v[232:235], v[86:89]
	v_mfma_f32_16x16x32_bf16 v[70:73], v[190:193], v[240:243], v[70:73]
	v_mfma_f32_16x16x32_bf16 v[114:117], v[198:201], v[206:209], v[114:117]
	v_mfma_f32_16x16x32_bf16 v[98:101], v[198:201], v[214:217], v[98:101]
	v_mfma_f32_16x16x32_bf16 v[82:85], v[198:201], v[232:235], v[82:85]
	v_mfma_f32_16x16x32_bf16 v[66:69], v[198:201], v[240:243], v[66:69]
	s_setprio 0
	s_barrier
; #define PG8_STAGE(bufoff, gbase, voff) do { _Pragma("unroll") for (int _i = 0; _i < 2; ++_i) \
;         __builtin_amdgcn_global_load_lds((const unsigned*)((const char*)(gbase) + (voff)[_i]), (LAS unsigned*)(lds + (bufoff) + ldsw + _i * 8192), 16, 0, 0); } while (0)
; #define PG8_LDA(dst, b, h) do { _Pragma("unroll") for (int m = 0; m < 4; ++m) _Pragma("unroll") for (int k = 0; k < 2; ++k) dst[m][k] = *(const LAS bf16x8*)(lds + PG8_SA(b, h) + aoff + m * 2048 + k * 1024); } while (0)
; #define PG8_MMA(ai, bj, At, Bt) do { __builtin_amdgcn_s_setprio(1); _Pragma("unroll") for (int m = 0; m < 4; ++m) _Pragma("unroll") for (int n = 0; n < 2; ++n) _Pragma("unroll") for (int k = 0; k < 2; ++k) \
;         acc[ai][bj][m][n] = __builtin_amdgcn_mfma_f32_16x16x32_bf16(Bt[n][k], At[m][k], acc[ai][bj][m][n], 0, 0, 0); __builtin_amdgcn_s_setprio(0); } while (0)
; #define PG8_WAIT_V(n) asm volatile("s_waitcnt vmcnt(" #n ")" ::: "memory")
; #define PG8_WAIT_L(n) asm volatile("s_waitcnt lgkmcnt(" #n ")" ::: "memory")
; #define PG8_BAR __builtin_amdgcn_s_barrier()
; #define PG8_SCHED __builtin_amdgcn_sched_barrier(0)
; template <class Epi>
; __device__ __forceinline__ void gemm_phase(LAS unsigned char* lds, const Gemm g, const StaticOrder& S, const Epi& E) {
;     ...
;             PG8_LDA(At, 1, 1); PG8_STAGE(PG8_SB(1, 0), b3, voffB); PG8_STAGE(PG8_SB(1, 1), b3 + hB, voffB); PG8_STAGE(PG8_SA(1, 0), a3, voffA);
;             PG8_WAIT_V(8); PG8_WAIT_L(0); PG8_BAR; PG8_MMA(1, 0, At, B0); PG8_MMA(1, 1, At, B1); PG8_BAR; PG8_SCHED;
;         }
;         if (wr == 0) PG8_BAR;
	s_add_i32 s36, s42, s51
	v_lshl_add_u64 v[178:179], v[178:179], 0, s[88:89]
	s_mov_b32 m0, s36
	ds_read_b128 v[202:205], v149 offset:49152
	ds_read_b128 v[206:209], v149 offset:50176
	ds_read_b128 v[210:213], v149 offset:51200
	ds_read_b128 v[214:217], v149 offset:52224
	ds_read_b128 v[218:221], v149 offset:53248
	ds_read_b128 v[232:235], v149 offset:54272
	ds_read_b128 v[236:239], v149 offset:55296
	ds_read_b128 v[240:243], v149 offset:56320
	global_load_lds_dwordx4 v[178:179], off
	s_add_i32 m0, s36, 0x2000
	s_add_u32 s34, s34, 0x40080
	v_lshl_add_u64 v[178:179], v[244:245], 0, s[88:89]
	s_addc_u32 s35, s35, 0
	s_add_i32 s36, s43, s51
	global_load_lds_dwordx4 v[178:179], off
	v_lshl_add_u64 v[178:179], s[34:35], 0, v[132:133]
	s_mov_b32 m0, s36
	s_nop 0
	global_load_lds_dwordx4 v[178:179], off
	v_lshl_add_u64 v[178:179], s[34:35], 0, v[136:137]
	s_add_i32 m0, s36, 0x2000
	s_nop 0
	global_load_lds_dwordx4 v[178:179], off
	v_lshl_add_u64 v[178:179], v[246:247], 0, s[88:89]
	s_mov_b32 m0, s60
	s_nop 0
	global_load_lds_dwordx4 v[178:179], off
	v_lshl_add_u64 v[178:179], v[248:249], 0, s[88:89]
	s_mov_b32 m0, s61
	s_nop 0
	global_load_lds_dwordx4 v[178:179], off
	s_waitcnt vmcnt(8)
	s_waitcnt lgkmcnt(0)
	s_barrier
	s_setprio 1
	v_mfma_f32_16x16x32_bf16 v[62:65], v[166:169], v[202:205], v[62:65]
	v_mfma_f32_16x16x32_bf16 v[46:49], v[166:169], v[210:213], v[46:49]
	v_mfma_f32_16x16x32_bf16 v[30:33], v[166:169], v[218:221], v[30:33]
	v_mfma_f32_16x16x32_bf16 v[14:17], v[166:169], v[236:239], v[14:17]
	v_mfma_f32_16x16x32_bf16 v[58:61], v[174:177], v[202:205], v[58:61]
	v_mfma_f32_16x16x32_bf16 v[42:45], v[174:177], v[210:213], v[42:45]
	v_mfma_f32_16x16x32_bf16 v[26:29], v[174:177], v[218:221], v[26:29]
	v_mfma_f32_16x16x32_bf16 v[10:13], v[174:177], v[236:239], v[10:13]
	v_mfma_f32_16x16x32_bf16 v[62:65], v[170:173], v[206:209], v[62:65]
	v_mfma_f32_16x16x32_bf16 v[46:49], v[170:173], v[214:217], v[46:49]
	v_mfma_f32_16x16x32_bf16 v[30:33], v[170:173], v[232:235], v[30:33]
	v_mfma_f32_16x16x32_bf16 v[14:17], v[170:173], v[240:243], v[14:17]
	v_mfma_f32_16x16x32_bf16 v[58:61], v[182:185], v[206:209], v[58:61]
	v_mfma_f32_16x16x32_bf16 v[42:45], v[182:185], v[214:217], v[42:45]
	v_mfma_f32_16x16x32_bf16 v[26:29], v[182:185], v[232:235], v[26:29]
	v_mfma_f32_16x16x32_bf16 v[10:13], v[182:185], v[240:243], v[10:13]
	v_mfma_f32_16x16x32_bf16 v[54:57], v[186:189], v[202:205], v[54:57]
	v_mfma_f32_16x16x32_bf16 v[38:41], v[186:189], v[210:213], v[38:41]
	v_mfma_f32_16x16x32_bf16 v[22:25], v[186:189], v[218:221], v[22:25]
	v_mfma_f32_16x16x32_bf16 v[6:9], v[186:189], v[236:239], v[6:9]
	v_mfma_f32_16x16x32_bf16 v[50:53], v[194:197], v[202:205], v[50:53]
	v_mfma_f32_16x16x32_bf16 v[34:37], v[194:197], v[210:213], v[34:37]
	v_mfma_f32_16x16x32_bf16 v[18:21], v[194:197], v[218:221], v[18:21]
	v_mfma_f32_16x16x32_bf16 v[2:5], v[194:197], v[236:239], v[2:5]
	v_mfma_f32_16x16x32_bf16 v[54:57], v[190:193], v[206:209], v[54:57]
	v_mfma_f32_16x16x32_bf16 v[38:41], v[190:193], v[214:217], v[38:41]
	v_mfma_f32_16x16x32_bf16 v[22:25], v[190:193], v[232:235], v[22:25]
	v_mfma_f32_16x16x32_bf16 v[6:9], v[190:193], v[240:243], v[6:9]
	v_mfma_f32_16x16x32_bf16 v[50:53], v[198:201], v[206:209], v[50:53]
	v_mfma_f32_16x16x32_bf16 v[34:37], v[198:201], v[214:217], v[34:37]
	v_mfma_f32_16x16x32_bf16 v[18:21], v[198:201], v[232:235], v[18:21]
	v_mfma_f32_16x16x32_bf16 v[2:5], v[198:201], v[240:243], v[2:5]
	s_setprio 0
	s_barrier
	s_add_i32 s41, s41, 2
	s_add_u32 s8, s8, 0x100
	s_addc_u32 s9, s9, 0
	s_add_u32 s39, s39, 0x100
	s_addc_u32 s40, s40, 0
	s_cmp_gt_u32 s41, 13
	s_cbranch_scc0 .LBB0_132
	s_and_b64 vcc, exec, s[16:17]
	s_cbranch_vccz .LBB0_135
	s_barrier

; #define PG8_STAGE(bufoff, gbase, voff) do { _Pragma("unroll") for (int _i = 0; _i < 2; ++_i) \
;         __builtin_amdgcn_global_load_lds((const unsigned*)((const char*)(gbase) + (voff)[_i]), (LAS unsigned*)(lds + (bufoff) + ldsw + _i * 8192), 16, 0, 0); } while (0)
; #define PG8_LDA(dst, b, h) do { _Pragma("unroll") for (int m = 0; m < 4; ++m) _Pragma("unroll") for (int k = 0; k < 2; ++k) dst[m][k] = *(const LAS bf16x8*)(lds + PG8_SA(b, h) + aoff + m * 2048 + k * 1024); } while (0)
; #define PG8_LDB(dst, b, h) do { _Pragma("unroll") for (int n = 0; n < 2; ++n) _Pragma("unroll") for (int k = 0; k < 2; ++k) dst[n][k] = *(const LAS bf16x8*)(lds + PG8_SB(b, h) + boff + n * 2048 + k * 1024); } while (0)
; #define PG8_MMA(ai, bj, At, Bt) do { __builtin_amdgcn_s_setprio(1); _Pragma("unroll") for (int m = 0; m < 4; ++m) _Pragma("unroll") for (int n = 0; n < 2; ++n) _Pragma("unroll") for (int k = 0; k < 2; ++k) \
;         acc[ai][bj][m][n] = __builtin_amdgcn_mfma_f32_16x16x32_bf16(Bt[n][k], At[m][k], acc[ai][bj][m][n], 0, 0, 0); __builtin_amdgcn_s_setprio(0); } while (0)
; #define PG8_WAIT_V(n) asm volatile("s_waitcnt vmcnt(" #n ")" ::: "memory")
; #define PG8_WAIT_L(n) asm volatile("s_waitcnt lgkmcnt(" #n ")" ::: "memory")
; #define PG8_BAR __builtin_amdgcn_s_barrier()
; #define PG8_SCHED __builtin_amdgcn_sched_barrier(0)
; template <class Epi>
; __device__ __forceinline__ void gemm_phase(LAS unsigned char* lds, const Gemm g, const StaticOrder& S, const Epi& E) {
;     ...
;             PG8_LDB(B0, 0, 0); PG8_LDB(B1, 0, 1); PG8_SCHED; PG8_LDA(At, 0, 0); PG8_STAGE(PG8_SA(1, 1), a1 + hA, voffA);
;             PG8_WAIT_V(8); PG8_WAIT_L(0); PG8_BAR; PG8_MMA(0, 0, At, B0); PG8_MMA(0, 1, At, B1); PG8_BAR; PG8_SCHED;
;             PG8_LDA(At, 0, 1); PG8_STAGE(PG8_SB(0, 0), b2, voffB); PG8_STAGE(PG8_SB(0, 1), b2 + hB, voffB); PG8_STAGE(PG8_SA(0, 0), a2, voffA);
.LBB0_518:
	s_add_u32 s30, s28, 0xfffc0080
	s_addc_u32 s31, s29, -1
	s_add_i32 s71, 0, 0x10000
	s_cmp_eq_u32 s70, 28
	s_cselect_b32 s35, s21, s31
	s_cselect_b32 s34, s27, s30
	v_add_u32_e32 v154, s71, v156
	s_cselect_b32 s31, s19, s67
	s_cselect_b32 s30, s65, s66
	s_add_i32 s73, 0, 0x14000
	ds_read_b128 v[98:101], v154
	ds_read_b128 v[102:105], v154 offset:1024
	ds_read_b128 v[158:161], v154 offset:2048
	ds_read_b128 v[162:165], v154 offset:3072
	v_add_u32_e32 v154, s73, v156
	ds_read_b128 v[166:169], v154
	ds_read_b128 v[170:173], v154 offset:1024
	ds_read_b128 v[174:177], v154 offset:2048
	ds_read_b128 v[182:185], v154 offset:3072
	v_lshl_add_u64 v[154:155], s[28:29], 0, v[150:151]
	s_add_i32 m0, s54, 0xc000
	ds_read_b128 v[186:189], v157
	ds_read_b128 v[190:193], v157 offset:1024
	ds_read_b128 v[194:197], v157 offset:2048
	ds_read_b128 v[198:201], v157 offset:3072
	ds_read_b128 v[202:205], v157 offset:4096
	ds_read_b128 v[206:209], v157 offset:5120
	ds_read_b128 v[210:213], v157 offset:6144
	ds_read_b128 v[214:217], v157 offset:7168
	global_load_lds_dwordx4 v[154:155], off
	v_lshl_add_u64 v[154:155], s[28:29], 0, v[152:153]
	s_add_i32 m0, s54, 0xe000
	s_nop 0
	global_load_lds_dwordx4 v[154:155], off
	s_waitcnt vmcnt(8)
	s_waitcnt lgkmcnt(0)
	s_barrier
	s_setprio 1
	v_mfma_f32_16x16x32_bf16 v[134:137], v[98:101], v[186:189], v[134:137]
	v_mfma_f32_16x16x32_bf16 v[126:129], v[98:101], v[194:197], v[126:129]
	v_mfma_f32_16x16x32_bf16 v[118:121], v[98:101], v[202:205], v[118:121]
	v_mfma_f32_16x16x32_bf16 v[110:113], v[98:101], v[210:213], v[110:113]
	v_mfma_f32_16x16x32_bf16 v[130:133], v[158:161], v[186:189], v[130:133]
	v_mfma_f32_16x16x32_bf16 v[122:125], v[158:161], v[194:197], v[122:125]
	v_mfma_f32_16x16x32_bf16 v[114:117], v[158:161], v[202:205], v[114:117]
	v_mfma_f32_16x16x32_bf16 v[106:109], v[158:161], v[210:213], v[106:109]
	v_mfma_f32_16x16x32_bf16 v[134:137], v[102:105], v[190:193], v[134:137]
	v_mfma_f32_16x16x32_bf16 v[126:129], v[102:105], v[198:201], v[126:129]
	v_mfma_f32_16x16x32_bf16 v[118:121], v[102:105], v[206:209], v[118:121]
	v_mfma_f32_16x16x32_bf16 v[110:113], v[102:105], v[214:217], v[110:113]
	v_mfma_f32_16x16x32_bf16 v[130:133], v[162:165], v[190:193], v[130:133]
	v_mfma_f32_16x16x32_bf16 v[122:125], v[162:165], v[198:201], v[122:125]
	v_mfma_f32_16x16x32_bf16 v[114:117], v[162:165], v[206:209], v[114:117]
	v_mfma_f32_16x16x32_bf16 v[106:109], v[162:165], v[214:217], v[106:109]
	v_mfma_f32_16x16x32_bf16 v[62:65], v[166:169], v[186:189], v[62:65]
	v_mfma_f32_16x16x32_bf16 v[54:57], v[166:169], v[194:197], v[54:57]
	v_mfma_f32_16x16x32_bf16 v[46:49], v[166:169], v[202:205], v[46:49]
	v_mfma_f32_16x16x32_bf16 v[38:41], v[166:169], v[210:213], v[38:41]
	v_mfma_f32_16x16x32_bf16 v[58:61], v[174:177], v[186:189], v[58:61]
	v_mfma_f32_16x16x32_bf16 v[50:53], v[174:177], v[194:197], v[50:53]
	v_mfma_f32_16x16x32_bf16 v[42:45], v[174:177], v[202:205], v[42:45]
	v_mfma_f32_16x16x32_bf16 v[34:37], v[174:177], v[210:213], v[34:37]
	v_mfma_f32_16x16x32_bf16 v[62:65], v[170:173], v[190:193], v[62:65]
	v_mfma_f32_16x16x32_bf16 v[54:57], v[170:173], v[198:201], v[54:57]
	v_mfma_f32_16x16x32_bf16 v[46:49], v[170:173], v[206:209], v[46:49]
	v_mfma_f32_16x16x32_bf16 v[38:41], v[170:173], v[214:217], v[38:41]
	v_mfma_f32_16x16x32_bf16 v[58:61], v[182:185], v[190:193], v[58:61]
	v_mfma_f32_16x16x32_bf16 v[50:53], v[182:185], v[198:201], v[50:53]
	v_mfma_f32_16x16x32_bf16 v[42:45], v[182:185], v[206:209], v[42:45]
	v_mfma_f32_16x16x32_bf16 v[34:37], v[182:185], v[214:217], v[34:37]
	s_setprio 0
	s_barrier
	s_add_i32 s71, s71, s53
	v_lshl_add_u64 v[154:155], s[30:31], 0, v[140:141]
	s_mov_b32 m0, s71
	ds_read_b128 v[186:189], v157 offset:16384
	ds_read_b128 v[190:193], v157 offset:17408
	ds_read_b128 v[194:197], v157 offset:18432
	ds_read_b128 v[198:201], v157 offset:19456
	ds_read_b128 v[202:205], v157 offset:20480
	ds_read_b128 v[206:209], v157 offset:21504
	ds_read_b128 v[210:213], v157 offset:22528
	ds_read_b128 v[214:217], v157 offset:23552
	global_load_lds_dwordx4 v[154:155], off
	s_add_i32 m0, s71, 0x2000
	s_add_u32 s74, s30, 0x80000
	v_lshl_add_u64 v[178:179], s[30:31], 0, v[144:145]
	s_addc_u32 s75, s31, 0
	s_add_i32 s71, s73, s53
	global_load_lds_dwordx4 v[178:179], off
	v_lshl_add_u64 v[218:219], s[74:75], 0, v[140:141]
	s_mov_b32 m0, s71
	v_lshl_add_u64 v[220:221], s[34:35], 0, v[142:143]
	global_load_lds_dwordx4 v[218:219], off
	v_lshl_add_u64 v[218:219], s[74:75], 0, v[144:145]
	s_add_i32 m0, s71, 0x2000
	s_nop 0
	global_load_lds_dwordx4 v[218:219], off
	v_lshl_add_u64 v[218:219], s[34:35], 0, v[138:139]
	s_mov_b32 m0, s54
	s_nop 0
	global_load_lds_dwordx4 v[218:219], off
	s_mov_b32 m0, s55
	s_nop 0
	global_load_lds_dwordx4 v[220:221], off
	s_waitcnt vmcnt(8)
	s_waitcnt lgkmcnt(0)
	s_barrier
; #define PG8_STAGE(bufoff, gbase, voff) do { _Pragma("unroll") for (int _i = 0; _i < 2; ++_i) \
;         __builtin_amdgcn_global_load_lds((const unsigned*)((const char*)(gbase) + (voff)[_i]), (LAS unsigned*)(lds + (bufoff) + ldsw + _i * 8192), 16, 0, 0); } while (0)
; #define PG8_LDA(dst, b, h) do { _Pragma("unroll") for (int m = 0; m < 4; ++m) _Pragma("unroll") for (int k = 0; k < 2; ++k) dst[m][k] = *(const LAS bf16x8*)(lds + PG8_SA(b, h) + aoff + m * 2048 + k * 1024); } while (0)
; #define PG8_LDB(dst, b, h) do { _Pragma("unroll") for (int n = 0; n < 2; ++n) _Pragma("unroll") for (int k = 0; k < 2; ++k) dst[n][k] = *(const LAS bf16x8*)(lds + PG8_SB(b, h) + boff + n * 2048 + k * 1024); } while (0)
; #define PG8_MMA(ai, bj, At, Bt) do { __builtin_amdgcn_s_setprio(1); _Pragma("unroll") for (int m = 0; m < 4; ++m) _Pragma("unroll") for (int n = 0; n < 2; ++n) _Pragma("unroll") for (int k = 0; k < 2; ++k) \
;         acc[ai][bj][m][n] = __builtin_amdgcn_mfma_f32_16x16x32_bf16(Bt[n][k], At[m][k], acc[ai][bj][m][n], 0, 0, 0); __builtin_amdgcn_s_setprio(0); } while (0)
; #define PG8_WAIT_V(n) asm volatile("s_waitcnt vmcnt(" #n ")" ::: "memory")
; #define PG8_WAIT_L(n) asm volatile("s_waitcnt lgkmcnt(" #n ")" ::: "memory")
; #define PG8_BAR __builtin_amdgcn_s_barrier()
; #define PG8_SCHED __builtin_amdgcn_sched_barrier(0)
; template <class Epi>
; __device__ __forceinline__ void gemm_phase(LAS unsigned char* lds, const Gemm g, const StaticOrder& S, const Epi& E) {
;     ...
;             PG8_WAIT_V(8); PG8_WAIT_L(0); PG8_BAR; PG8_MMA(1, 0, At, B0); PG8_MMA(1, 1, At, B1); PG8_BAR; PG8_SCHED;
;             PG8_LDB(B0, 1, 0); PG8_LDB(B1, 1, 1); PG8_SCHED; PG8_LDA(At, 1, 0); PG8_STAGE(PG8_SA(0, 1), a2 + hA, voffA);
;             PG8_WAIT_V(8); PG8_WAIT_L(0); PG8_BAR; PG8_MMA(0, 0, At, B0); PG8_MMA(0, 1, At, B1); PG8_BAR; PG8_SCHED;
	s_setprio 1
	v_mfma_f32_16x16x32_bf16 v[94:97], v[98:101], v[186:189], v[94:97]
	v_mfma_f32_16x16x32_bf16 v[86:89], v[98:101], v[194:197], v[86:89]
	v_mfma_f32_16x16x32_bf16 v[78:81], v[98:101], v[202:205], v[78:81]
	v_mfma_f32_16x16x32_bf16 v[70:73], v[98:101], v[210:213], v[70:73]
	v_mfma_f32_16x16x32_bf16 v[90:93], v[158:161], v[186:189], v[90:93]
	v_mfma_f32_16x16x32_bf16 v[82:85], v[158:161], v[194:197], v[82:85]
	v_mfma_f32_16x16x32_bf16 v[74:77], v[158:161], v[202:205], v[74:77]
	v_mfma_f32_16x16x32_bf16 v[66:69], v[158:161], v[210:213], v[66:69]
	v_mfma_f32_16x16x32_bf16 v[94:97], v[102:105], v[190:193], v[94:97]
	v_mfma_f32_16x16x32_bf16 v[86:89], v[102:105], v[198:201], v[86:89]
	v_mfma_f32_16x16x32_bf16 v[78:81], v[102:105], v[206:209], v[78:81]
	v_mfma_f32_16x16x32_bf16 v[70:73], v[102:105], v[214:217], v[70:73]
	v_mfma_f32_16x16x32_bf16 v[90:93], v[162:165], v[190:193], v[90:93]
	v_mfma_f32_16x16x32_bf16 v[82:85], v[162:165], v[198:201], v[82:85]
	v_mfma_f32_16x16x32_bf16 v[74:77], v[162:165], v[206:209], v[74:77]
	v_mfma_f32_16x16x32_bf16 v[66:69], v[162:165], v[214:217], v[66:69]
	v_mfma_f32_16x16x32_bf16 v[30:33], v[166:169], v[186:189], v[30:33]
	v_mfma_f32_16x16x32_bf16 v[22:25], v[166:169], v[194:197], v[22:25]
	v_mfma_f32_16x16x32_bf16 v[14:17], v[166:169], v[202:205], v[14:17]
	v_mfma_f32_16x16x32_bf16 v[6:9], v[166:169], v[210:213], v[6:9]
	v_mfma_f32_16x16x32_bf16 v[26:29], v[174:177], v[186:189], v[26:29]
	v_mfma_f32_16x16x32_bf16 v[18:21], v[174:177], v[194:197], v[18:21]
	v_mfma_f32_16x16x32_bf16 v[10:13], v[174:177], v[202:205], v[10:13]
	v_mfma_f32_16x16x32_bf16 v[2:5], v[174:177], v[210:213], v[2:5]
	v_mfma_f32_16x16x32_bf16 v[30:33], v[170:173], v[190:193], v[30:33]
	v_mfma_f32_16x16x32_bf16 v[22:25], v[170:173], v[198:201], v[22:25]
	v_mfma_f32_16x16x32_bf16 v[14:17], v[170:173], v[206:209], v[14:17]
	v_mfma_f32_16x16x32_bf16 v[6:9], v[170:173], v[214:217], v[6:9]
	v_mfma_f32_16x16x32_bf16 v[26:29], v[182:185], v[190:193], v[26:29]
	v_mfma_f32_16x16x32_bf16 v[18:21], v[182:185], v[198:201], v[18:21]
	v_mfma_f32_16x16x32_bf16 v[10:13], v[182:185], v[206:209], v[10:13]
	v_mfma_f32_16x16x32_bf16 v[2:5], v[182:185], v[214:217], v[2:5]
	s_setprio 0
	s_barrier
	s_add_i32 s71, 0, 0x18000
	s_add_i32 s73, 0, 0x1c000
	v_add_u32_e32 v162, s71, v156
	v_add_u32_e32 v180, s73, v156
	ds_read_b128 v[98:101], v162
	ds_read_b128 v[102:105], v162 offset:1024
	ds_read_b128 v[158:161], v162 offset:2048
	ds_read_b128 v[162:165], v162 offset:3072
	ds_read_b128 v[166:169], v180
	ds_read_b128 v[170:173], v180 offset:1024
	ds_read_b128 v[174:177], v180 offset:2048
	ds_read_b128 v[182:185], v180 offset:3072
	s_add_u32 s34, s34, 0x40000
	s_addc_u32 s35, s35, 0
	s_mov_b32 m0, s56
	v_lshl_add_u64 v[232:233], s[34:35], 0, v[138:139]
	ds_read_b128 v[186:189], v157 offset:32768
	ds_read_b128 v[190:193], v157 offset:33792
	ds_read_b128 v[194:197], v157 offset:34816
	ds_read_b128 v[198:201], v157 offset:35840
	ds_read_b128 v[202:205], v157 offset:36864
	ds_read_b128 v[206:209], v157 offset:37888
	ds_read_b128 v[210:213], v157 offset:38912
	ds_read_b128 v[214:217], v157 offset:39936
	global_load_lds_dwordx4 v[232:233], off
	v_lshl_add_u64 v[232:233], s[34:35], 0, v[142:143]
	s_mov_b32 m0, s57
	s_nop 0
	global_load_lds_dwordx4 v[232:233], off
	s_waitcnt vmcnt(8)
	s_waitcnt lgkmcnt(0)
	s_barrier
	s_setprio 1
	v_mfma_f32_16x16x32_bf16 v[134:137], v[98:101], v[186:189], v[134:137]
	v_mfma_f32_16x16x32_bf16 v[126:129], v[98:101], v[194:197], v[126:129]
	v_mfma_f32_16x16x32_bf16 v[118:121], v[98:101], v[202:205], v[118:121]
	v_mfma_f32_16x16x32_bf16 v[110:113], v[98:101], v[210:213], v[110:113]
	v_mfma_f32_16x16x32_bf16 v[130:133], v[158:161], v[186:189], v[130:133]
	v_mfma_f32_16x16x32_bf16 v[122:125], v[158:161], v[194:197], v[122:125]
	v_mfma_f32_16x16x32_bf16 v[114:117], v[158:161], v[202:205], v[114:117]
	v_mfma_f32_16x16x32_bf16 v[106:109], v[158:161], v[210:213], v[106:109]
	v_mfma_f32_16x16x32_bf16 v[134:137], v[102:105], v[190:193], v[134:137]
	v_mfma_f32_16x16x32_bf16 v[126:129], v[102:105], v[198:201], v[126:129]
	v_mfma_f32_16x16x32_bf16 v[118:121], v[102:105], v[206:209], v[118:121]
	v_mfma_f32_16x16x32_bf16 v[110:113], v[102:105], v[214:217], v[110:113]
	v_mfma_f32_16x16x32_bf16 v[130:133], v[162:165], v[190:193], v[130:133]
	v_mfma_f32_16x16x32_bf16 v[122:125], v[162:165], v[198:201], v[122:125]
	v_mfma_f32_16x16x32_bf16 v[114:117], v[162:165], v[206:209], v[114:117]
	v_mfma_f32_16x16x32_bf16 v[106:109], v[162:165], v[214:217], v[106:109]
	v_mfma_f32_16x16x32_bf16 v[62:65], v[166:169], v[186:189], v[62:65]
	v_mfma_f32_16x16x32_bf16 v[54:57], v[166:169], v[194:197], v[54:57]
	v_mfma_f32_16x16x32_bf16 v[46:49], v[166:169], v[202:205], v[46:49]
	v_mfma_f32_16x16x32_bf16 v[38:41], v[166:169], v[210:213], v[38:41]
	v_mfma_f32_16x16x32_bf16 v[58:61], v[174:177], v[186:189], v[58:61]
	v_mfma_f32_16x16x32_bf16 v[50:53], v[174:177], v[194:197], v[50:53]
	v_mfma_f32_16x16x32_bf16 v[42:45], v[174:177], v[202:205], v[42:45]
	v_mfma_f32_16x16x32_bf16 v[34:37], v[174:177], v[210:213], v[34:37]
	v_mfma_f32_16x16x32_bf16 v[62:65], v[170:173], v[190:193], v[62:65]
	v_mfma_f32_16x16x32_bf16 v[54:57], v[170:173], v[198:201], v[54:57]
	v_mfma_f32_16x16x32_bf16 v[46:49], v[170:173], v[206:209], v[46:49]
	v_mfma_f32_16x16x32_bf16 v[38:41], v[170:173], v[214:217], v[38:41]
	v_mfma_f32_16x16x32_bf16 v[58:61], v[182:185], v[190:193], v[58:61]
	v_mfma_f32_16x16x32_bf16 v[50:53], v[182:185], v[198:201], v[50:53]
	v_mfma_f32_16x16x32_bf16 v[42:45], v[182:185], v[206:209], v[42:45]
	v_mfma_f32_16x16x32_bf16 v[34:37], v[182:185], v[214:217], v[34:37]
	s_setprio 0
	s_barrier
; #define PG8_STAGE(bufoff, gbase, voff) do { _Pragma("unroll") for (int _i = 0; _i < 2; ++_i) \
;         __builtin_amdgcn_global_load_lds((const unsigned*)((const char*)(gbase) + (voff)[_i]), (LAS unsigned*)(lds + (bufoff) + ldsw + _i * 8192), 16, 0, 0); } while (0)
; #define PG8_LDA(dst, b, h) do { _Pragma("unroll") for (int m = 0; m < 4; ++m) _Pragma("unroll") for (int k = 0; k < 2; ++k) dst[m][k] = *(const LAS bf16x8*)(lds + PG8_SA(b, h) + aoff + m * 2048 + k * 1024); } while (0)
; #define PG8_MMA(ai, bj, At, Bt) do { __builtin_amdgcn_s_setprio(1); _Pragma("unroll") for (int m = 0; m < 4; ++m) _Pragma("unroll") for (int n = 0; n < 2; ++n) _Pragma("unroll") for (int k = 0; k < 2; ++k) \
;         acc[ai][bj][m][n] = __builtin_amdgcn_mfma_f32_16x16x32_bf16(Bt[n][k], At[m][k], acc[ai][bj][m][n], 0, 0, 0); __builtin_amdgcn_s_setprio(0); } while (0)
; #define PG8_WAIT_V(n) asm volatile("s_waitcnt vmcnt(" #n ")" ::: "memory")
; #define PG8_WAIT_L(n) asm volatile("s_waitcnt lgkmcnt(" #n ")" ::: "memory")
; #define PG8_BAR __builtin_amdgcn_s_barrier()
; #define PG8_SCHED __builtin_amdgcn_sched_barrier(0)
; template <class Epi>
; __device__ __forceinline__ void gemm_phase(LAS unsigned char* lds, const Gemm g, const StaticOrder& S, const Epi& E) {
;     ...
;             PG8_LDA(At, 1, 1); PG8_STAGE(PG8_SB(1, 0), b3, voffB); PG8_STAGE(PG8_SB(1, 1), b3 + hB, voffB); PG8_STAGE(PG8_SA(1, 0), a3, voffA);
;             PG8_WAIT_V(8); PG8_WAIT_L(0); PG8_BAR; PG8_MMA(1, 0, At, B0); PG8_MMA(1, 1, At, B1); PG8_BAR; PG8_SCHED;
;         }
;         if (wr == 0) PG8_BAR;
	s_add_i32 s34, s71, s53
	v_lshl_add_u64 v[154:155], v[154:155], 0, s[88:89]
	s_mov_b32 m0, s34
	ds_read_b128 v[186:189], v157 offset:49152
	ds_read_b128 v[190:193], v157 offset:50176
	ds_read_b128 v[194:197], v157 offset:51200
	ds_read_b128 v[198:201], v157 offset:52224
	ds_read_b128 v[202:205], v157 offset:53248
	ds_read_b128 v[206:209], v157 offset:54272
	ds_read_b128 v[210:213], v157 offset:55296
	ds_read_b128 v[214:217], v157 offset:56320
	global_load_lds_dwordx4 v[154:155], off
	s_add_i32 m0, s34, 0x2000
	s_add_u32 s30, s30, 0x80080
	v_lshl_add_u64 v[154:155], v[178:179], 0, s[88:89]
	s_addc_u32 s31, s31, 0
	s_add_i32 s34, s73, s53
	global_load_lds_dwordx4 v[154:155], off
	v_lshl_add_u64 v[154:155], s[30:31], 0, v[140:141]
	s_mov_b32 m0, s34
	s_nop 0
	global_load_lds_dwordx4 v[154:155], off
	v_lshl_add_u64 v[154:155], s[30:31], 0, v[144:145]
	s_add_i32 m0, s34, 0x2000
	s_nop 0
	global_load_lds_dwordx4 v[154:155], off
	v_lshl_add_u64 v[154:155], v[218:219], 0, s[88:89]
	s_mov_b32 m0, s59
	s_nop 0
	global_load_lds_dwordx4 v[154:155], off
	v_lshl_add_u64 v[154:155], v[220:221], 0, s[88:89]
	s_mov_b32 m0, s60
	s_nop 0
	global_load_lds_dwordx4 v[154:155], off
	s_waitcnt vmcnt(8)
	s_waitcnt lgkmcnt(0)
	s_barrier
	s_setprio 1
	v_mfma_f32_16x16x32_bf16 v[94:97], v[98:101], v[186:189], v[94:97]
	v_mfma_f32_16x16x32_bf16 v[86:89], v[98:101], v[194:197], v[86:89]
	v_mfma_f32_16x16x32_bf16 v[78:81], v[98:101], v[202:205], v[78:81]
	v_mfma_f32_16x16x32_bf16 v[70:73], v[98:101], v[210:213], v[70:73]
	v_mfma_f32_16x16x32_bf16 v[90:93], v[158:161], v[186:189], v[90:93]
	v_mfma_f32_16x16x32_bf16 v[82:85], v[158:161], v[194:197], v[82:85]
	v_mfma_f32_16x16x32_bf16 v[74:77], v[158:161], v[202:205], v[74:77]
	v_mfma_f32_16x16x32_bf16 v[66:69], v[158:161], v[210:213], v[66:69]
	v_mfma_f32_16x16x32_bf16 v[94:97], v[102:105], v[190:193], v[94:97]
	v_mfma_f32_16x16x32_bf16 v[86:89], v[102:105], v[198:201], v[86:89]
	v_mfma_f32_16x16x32_bf16 v[78:81], v[102:105], v[206:209], v[78:81]
	v_mfma_f32_16x16x32_bf16 v[70:73], v[102:105], v[214:217], v[70:73]
	v_mfma_f32_16x16x32_bf16 v[90:93], v[162:165], v[190:193], v[90:93]
	v_mfma_f32_16x16x32_bf16 v[82:85], v[162:165], v[198:201], v[82:85]
	v_mfma_f32_16x16x32_bf16 v[74:77], v[162:165], v[206:209], v[74:77]
	v_mfma_f32_16x16x32_bf16 v[66:69], v[162:165], v[214:217], v[66:69]
	v_mfma_f32_16x16x32_bf16 v[30:33], v[166:169], v[186:189], v[30:33]
	v_mfma_f32_16x16x32_bf16 v[22:25], v[166:169], v[194:197], v[22:25]
	v_mfma_f32_16x16x32_bf16 v[14:17], v[166:169], v[202:205], v[14:17]
	v_mfma_f32_16x16x32_bf16 v[6:9], v[166:169], v[210:213], v[6:9]
	v_mfma_f32_16x16x32_bf16 v[26:29], v[174:177], v[186:189], v[26:29]
	v_mfma_f32_16x16x32_bf16 v[18:21], v[174:177], v[194:197], v[18:21]
	v_mfma_f32_16x16x32_bf16 v[10:13], v[174:177], v[202:205], v[10:13]
	v_mfma_f32_16x16x32_bf16 v[2:5], v[174:177], v[210:213], v[2:5]
	v_mfma_f32_16x16x32_bf16 v[30:33], v[170:173], v[190:193], v[30:33]
	v_mfma_f32_16x16x32_bf16 v[22:25], v[170:173], v[198:201], v[22:25]
	v_mfma_f32_16x16x32_bf16 v[14:17], v[170:173], v[206:209], v[14:17]
	v_mfma_f32_16x16x32_bf16 v[6:9], v[170:173], v[214:217], v[6:9]
	v_mfma_f32_16x16x32_bf16 v[26:29], v[182:185], v[190:193], v[26:29]
	v_mfma_f32_16x16x32_bf16 v[18:21], v[182:185], v[198:201], v[18:21]
	v_mfma_f32_16x16x32_bf16 v[10:13], v[182:185], v[206:209], v[10:13]
	v_mfma_f32_16x16x32_bf16 v[2:5], v[182:185], v[214:217], v[2:5]
	s_setprio 0
	s_barrier
	s_add_i32 s70, s70, 2
	s_add_u32 s28, s28, 0x100
	s_addc_u32 s29, s29, 0
	s_add_u32 s66, s66, 0x100
	s_addc_u32 s67, s67, 0
	s_cmp_gt_u32 s70, 29
	s_cbranch_scc0 .LBB0_518
	s_and_b64 vcc, exec, s[16:17]
	s_cbranch_vccz .LBB0_521
	s_barrier

; #define PG8_STAGE(bufoff, gbase, voff) do { _Pragma("unroll") for (int _i = 0; _i < 2; ++_i) \
;         __builtin_amdgcn_global_load_lds((const unsigned*)((const char*)(gbase) + (voff)[_i]), (LAS unsigned*)(lds + (bufoff) + ldsw + _i * 8192), 16, 0, 0); } while (0)
; #define PG8_LDA(dst, b, h) do { _Pragma("unroll") for (int m = 0; m < 4; ++m) _Pragma("unroll") for (int k = 0; k < 2; ++k) dst[m][k] = *(const LAS bf16x8*)(lds + PG8_SA(b, h) + aoff + m * 2048 + k * 1024); } while (0)
; #define PG8_LDB(dst, b, h) do { _Pragma("unroll") for (int n = 0; n < 2; ++n) _Pragma("unroll") for (int k = 0; k < 2; ++k) dst[n][k] = *(const LAS bf16x8*)(lds + PG8_SB(b, h) + boff + n * 2048 + k * 1024); } while (0)
; #define PG8_MMA(ai, bj, At, Bt) do { __builtin_amdgcn_s_setprio(1); _Pragma("unroll") for (int m = 0; m < 4; ++m) _Pragma("unroll") for (int n = 0; n < 2; ++n) _Pragma("unroll") for (int k = 0; k < 2; ++k) \
;         acc[ai][bj][m][n] = __builtin_amdgcn_mfma_f32_16x16x32_bf16(Bt[n][k], At[m][k], acc[ai][bj][m][n], 0, 0, 0); __builtin_amdgcn_s_setprio(0); } while (0)
; #define PG8_WAIT_V(n) asm volatile("s_waitcnt vmcnt(" #n ")" ::: "memory")
; #define PG8_WAIT_L(n) asm volatile("s_waitcnt lgkmcnt(" #n ")" ::: "memory")
; #define PG8_BAR __builtin_amdgcn_s_barrier()
; #define PG8_SCHED __builtin_amdgcn_sched_barrier(0)
; template <class Epi>
; __device__ __forceinline__ void gemm_phase(LAS unsigned char* lds, const Gemm g, const StaticOrder& S, const Epi& E) {
;     ...
;             PG8_LDB(B0, 0, 0); PG8_LDB(B1, 0, 1); PG8_SCHED; PG8_LDA(At, 0, 0); PG8_STAGE(PG8_SA(1, 1), a1 + hA, voffA);
;             PG8_WAIT_V(8); PG8_WAIT_L(0); PG8_BAR; PG8_MMA(0, 0, At, B0); PG8_MMA(0, 1, At, B1); PG8_BAR; PG8_SCHED;
;             PG8_LDA(At, 0, 1); PG8_STAGE(PG8_SB(0, 0), b2, voffB); PG8_STAGE(PG8_SB(0, 1), b2 + hB, voffB); PG8_STAGE(PG8_SA(0, 0), a2, voffA);
.LBB0_1398:
	s_add_u32 s10, s8, 0xfffc0080
	s_addc_u32 s11, s9, -1
	s_add_i32 s35, 0, 0x10000
	s_cmp_eq_u32 s31, 12
	s_cselect_b32 s41, s37, s11
	s_cselect_b32 s40, s36, s10
	s_cselect_b32 s11, s39, s29
	s_cselect_b32 s10, s38, s27
	s_add_i32 s64, 0, 0x14000
	v_add_u32_e32 v158, s35, v180
	v_add_u32_e32 v174, s64, v180
	ds_read_b128 v[146:149], v158
	ds_read_b128 v[150:153], v158 offset:1024
	ds_read_b128 v[154:157], v158 offset:2048
	ds_read_b128 v[158:161], v158 offset:3072
	ds_read_b128 v[162:165], v174
	ds_read_b128 v[166:169], v174 offset:1024
	ds_read_b128 v[170:173], v174 offset:2048
	ds_read_b128 v[174:177], v174 offset:3072
	v_lshl_add_u64 v[178:179], s[8:9], 0, v[142:143]
	s_add_i32 m0, s51, 0xc000
	ds_read_b128 v[182:185], v211
	ds_read_b128 v[186:189], v211 offset:1024
	ds_read_b128 v[190:193], v211 offset:2048
	ds_read_b128 v[194:197], v211 offset:3072
	ds_read_b128 v[198:201], v211 offset:4096
	ds_read_b128 v[202:205], v211 offset:5120
	ds_read_b128 v[216:219], v211 offset:6144
	ds_read_b128 v[232:235], v211 offset:7168
	global_load_lds_dwordx4 v[178:179], off
	v_lshl_add_u64 v[178:179], s[8:9], 0, v[144:145]
	s_add_i32 m0, s51, 0xe000
	s_nop 0
	global_load_lds_dwordx4 v[178:179], off
	s_waitcnt vmcnt(8)
	s_waitcnt lgkmcnt(0)
	s_barrier
	s_setprio 1
	v_mfma_f32_16x16x32_bf16 v[126:129], v[146:149], v[182:185], v[126:129]
	v_mfma_f32_16x16x32_bf16 v[110:113], v[146:149], v[190:193], v[110:113]
	v_mfma_f32_16x16x32_bf16 v[94:97], v[146:149], v[198:201], v[94:97]
	v_mfma_f32_16x16x32_bf16 v[78:81], v[146:149], v[216:219], v[78:81]
	v_mfma_f32_16x16x32_bf16 v[122:125], v[154:157], v[182:185], v[122:125]
	v_mfma_f32_16x16x32_bf16 v[106:109], v[154:157], v[190:193], v[106:109]
	v_mfma_f32_16x16x32_bf16 v[90:93], v[154:157], v[198:201], v[90:93]
	v_mfma_f32_16x16x32_bf16 v[74:77], v[154:157], v[216:219], v[74:77]
	v_mfma_f32_16x16x32_bf16 v[126:129], v[150:153], v[186:189], v[126:129]
	v_mfma_f32_16x16x32_bf16 v[110:113], v[150:153], v[194:197], v[110:113]
	v_mfma_f32_16x16x32_bf16 v[94:97], v[150:153], v[202:205], v[94:97]
	v_mfma_f32_16x16x32_bf16 v[78:81], v[150:153], v[232:235], v[78:81]
	v_mfma_f32_16x16x32_bf16 v[122:125], v[158:161], v[186:189], v[122:125]
	v_mfma_f32_16x16x32_bf16 v[106:109], v[158:161], v[194:197], v[106:109]
	v_mfma_f32_16x16x32_bf16 v[90:93], v[158:161], v[202:205], v[90:93]
	v_mfma_f32_16x16x32_bf16 v[74:77], v[158:161], v[232:235], v[74:77]
	v_mfma_f32_16x16x32_bf16 v[118:121], v[162:165], v[182:185], v[118:121]
	v_mfma_f32_16x16x32_bf16 v[102:105], v[162:165], v[190:193], v[102:105]
	v_mfma_f32_16x16x32_bf16 v[86:89], v[162:165], v[198:201], v[86:89]
	v_mfma_f32_16x16x32_bf16 v[70:73], v[162:165], v[216:219], v[70:73]
	v_mfma_f32_16x16x32_bf16 v[114:117], v[170:173], v[182:185], v[114:117]
	v_mfma_f32_16x16x32_bf16 v[98:101], v[170:173], v[190:193], v[98:101]
	v_mfma_f32_16x16x32_bf16 v[82:85], v[170:173], v[198:201], v[82:85]
	v_mfma_f32_16x16x32_bf16 v[66:69], v[170:173], v[216:219], v[66:69]
	v_mfma_f32_16x16x32_bf16 v[118:121], v[166:169], v[186:189], v[118:121]
	v_mfma_f32_16x16x32_bf16 v[102:105], v[166:169], v[194:197], v[102:105]
	v_mfma_f32_16x16x32_bf16 v[86:89], v[166:169], v[202:205], v[86:89]
	v_mfma_f32_16x16x32_bf16 v[70:73], v[166:169], v[232:235], v[70:73]
	v_mfma_f32_16x16x32_bf16 v[114:117], v[174:177], v[186:189], v[114:117]
	v_mfma_f32_16x16x32_bf16 v[98:101], v[174:177], v[194:197], v[98:101]
	v_mfma_f32_16x16x32_bf16 v[82:85], v[174:177], v[202:205], v[82:85]
	v_mfma_f32_16x16x32_bf16 v[66:69], v[174:177], v[232:235], v[66:69]
	s_setprio 0
	s_barrier
	s_add_i32 s35, s35, s50
	v_lshl_add_u64 v[178:179], s[10:11], 0, v[132:133]
	s_mov_b32 m0, s35
	ds_read_b128 v[182:185], v211 offset:16384
	ds_read_b128 v[186:189], v211 offset:17408
	ds_read_b128 v[190:193], v211 offset:18432
	ds_read_b128 v[194:197], v211 offset:19456
	ds_read_b128 v[198:201], v211 offset:20480
	ds_read_b128 v[202:205], v211 offset:21504
	ds_read_b128 v[216:219], v211 offset:22528
	ds_read_b128 v[232:235], v211 offset:23552
	global_load_lds_dwordx4 v[178:179], off
	s_add_i32 m0, s35, 0x2000
	s_add_u32 s42, s10, 0x40000
	v_lshl_add_u64 v[206:207], s[10:11], 0, v[136:137]
	s_addc_u32 s43, s11, 0
	s_add_i32 s35, s64, s50
	global_load_lds_dwordx4 v[206:207], off
	v_lshl_add_u64 v[220:221], s[42:43], 0, v[132:133]
	s_mov_b32 m0, s35
	v_lshl_add_u64 v[236:237], s[40:41], 0, v[134:135]
	global_load_lds_dwordx4 v[220:221], off
	v_lshl_add_u64 v[220:221], s[42:43], 0, v[136:137]
	s_add_i32 m0, s35, 0x2000
	s_nop 0
	global_load_lds_dwordx4 v[220:221], off
	v_lshl_add_u64 v[220:221], s[40:41], 0, v[130:131]
	s_mov_b32 m0, s51
	s_nop 0
	global_load_lds_dwordx4 v[220:221], off
	s_mov_b32 m0, s52
	s_nop 0
	global_load_lds_dwordx4 v[236:237], off
	s_waitcnt vmcnt(8)
	s_waitcnt lgkmcnt(0)
	s_barrier
; #define PG8_STAGE(bufoff, gbase, voff) do { _Pragma("unroll") for (int _i = 0; _i < 2; ++_i) \
;         __builtin_amdgcn_global_load_lds((const unsigned*)((const char*)(gbase) + (voff)[_i]), (LAS unsigned*)(lds + (bufoff) + ldsw + _i * 8192), 16, 0, 0); } while (0)
; #define PG8_LDA(dst, b, h) do { _Pragma("unroll") for (int m = 0; m < 4; ++m) _Pragma("unroll") for (int k = 0; k < 2; ++k) dst[m][k] = *(const LAS bf16x8*)(lds + PG8_SA(b, h) + aoff + m * 2048 + k * 1024); } while (0)
; #define PG8_LDB(dst, b, h) do { _Pragma("unroll") for (int n = 0; n < 2; ++n) _Pragma("unroll") for (int k = 0; k < 2; ++k) dst[n][k] = *(const LAS bf16x8*)(lds + PG8_SB(b, h) + boff + n * 2048 + k * 1024); } while (0)
; #define PG8_MMA(ai, bj, At, Bt) do { __builtin_amdgcn_s_setprio(1); _Pragma("unroll") for (int m = 0; m < 4; ++m) _Pragma("unroll") for (int n = 0; n < 2; ++n) _Pragma("unroll") for (int k = 0; k < 2; ++k) \
;         acc[ai][bj][m][n] = __builtin_amdgcn_mfma_f32_16x16x32_bf16(Bt[n][k], At[m][k], acc[ai][bj][m][n], 0, 0, 0); __builtin_amdgcn_s_setprio(0); } while (0)
; #define PG8_WAIT_V(n) asm volatile("s_waitcnt vmcnt(" #n ")" ::: "memory")
; #define PG8_WAIT_L(n) asm volatile("s_waitcnt lgkmcnt(" #n ")" ::: "memory")
; #define PG8_BAR __builtin_amdgcn_s_barrier()
; #define PG8_SCHED __builtin_amdgcn_sched_barrier(0)
; template <class Epi>
; __device__ __forceinline__ void gemm_phase(LAS unsigned char* lds, const Gemm g, const StaticOrder& S, const Epi& E) {
;     ...
;             PG8_WAIT_V(8); PG8_WAIT_L(0); PG8_BAR; PG8_MMA(1, 0, At, B0); PG8_MMA(1, 1, At, B1); PG8_BAR; PG8_SCHED;
;             PG8_LDB(B0, 1, 0); PG8_LDB(B1, 1, 1); PG8_SCHED; PG8_LDA(At, 1, 0); PG8_STAGE(PG8_SA(0, 1), a2 + hA, voffA);
;             PG8_WAIT_V(8); PG8_WAIT_L(0); PG8_BAR; PG8_MMA(0, 0, At, B0); PG8_MMA(0, 1, At, B1); PG8_BAR; PG8_SCHED;
	s_setprio 1
	v_mfma_f32_16x16x32_bf16 v[62:65], v[146:149], v[182:185], v[62:65]
	v_mfma_f32_16x16x32_bf16 v[46:49], v[146:149], v[190:193], v[46:49]
	v_mfma_f32_16x16x32_bf16 v[30:33], v[146:149], v[198:201], v[30:33]
	v_mfma_f32_16x16x32_bf16 v[14:17], v[146:149], v[216:219], v[14:17]
	v_mfma_f32_16x16x32_bf16 v[58:61], v[154:157], v[182:185], v[58:61]
	v_mfma_f32_16x16x32_bf16 v[42:45], v[154:157], v[190:193], v[42:45]
	v_mfma_f32_16x16x32_bf16 v[26:29], v[154:157], v[198:201], v[26:29]
	v_mfma_f32_16x16x32_bf16 v[10:13], v[154:157], v[216:219], v[10:13]
	v_mfma_f32_16x16x32_bf16 v[62:65], v[150:153], v[186:189], v[62:65]
	v_mfma_f32_16x16x32_bf16 v[46:49], v[150:153], v[194:197], v[46:49]
	v_mfma_f32_16x16x32_bf16 v[30:33], v[150:153], v[202:205], v[30:33]
	v_mfma_f32_16x16x32_bf16 v[14:17], v[150:153], v[232:235], v[14:17]
	v_mfma_f32_16x16x32_bf16 v[58:61], v[158:161], v[186:189], v[58:61]
	v_mfma_f32_16x16x32_bf16 v[42:45], v[158:161], v[194:197], v[42:45]
	v_mfma_f32_16x16x32_bf16 v[26:29], v[158:161], v[202:205], v[26:29]
	v_mfma_f32_16x16x32_bf16 v[10:13], v[158:161], v[232:235], v[10:13]
	v_mfma_f32_16x16x32_bf16 v[54:57], v[162:165], v[182:185], v[54:57]
	v_mfma_f32_16x16x32_bf16 v[38:41], v[162:165], v[190:193], v[38:41]
	v_mfma_f32_16x16x32_bf16 v[22:25], v[162:165], v[198:201], v[22:25]
	v_mfma_f32_16x16x32_bf16 v[6:9], v[162:165], v[216:219], v[6:9]
	v_mfma_f32_16x16x32_bf16 v[50:53], v[170:173], v[182:185], v[50:53]
	v_mfma_f32_16x16x32_bf16 v[34:37], v[170:173], v[190:193], v[34:37]
	v_mfma_f32_16x16x32_bf16 v[18:21], v[170:173], v[198:201], v[18:21]
	v_mfma_f32_16x16x32_bf16 v[2:5], v[170:173], v[216:219], v[2:5]
	v_mfma_f32_16x16x32_bf16 v[54:57], v[166:169], v[186:189], v[54:57]
	v_mfma_f32_16x16x32_bf16 v[38:41], v[166:169], v[194:197], v[38:41]
	v_mfma_f32_16x16x32_bf16 v[22:25], v[166:169], v[202:205], v[22:25]
	v_mfma_f32_16x16x32_bf16 v[6:9], v[166:169], v[232:235], v[6:9]
	v_mfma_f32_16x16x32_bf16 v[50:53], v[174:177], v[186:189], v[50:53]
	v_mfma_f32_16x16x32_bf16 v[34:37], v[174:177], v[194:197], v[34:37]
	v_mfma_f32_16x16x32_bf16 v[18:21], v[174:177], v[202:205], v[18:21]
	v_mfma_f32_16x16x32_bf16 v[2:5], v[174:177], v[232:235], v[2:5]
	s_setprio 0
	s_barrier
	s_add_i32 s35, 0, 0x18000
	s_add_i32 s42, 0, 0x1c000
	v_add_u32_e32 v158, s35, v180
	v_add_u32_e32 v174, s42, v180
	ds_read_b128 v[146:149], v158
	ds_read_b128 v[150:153], v158 offset:1024
	ds_read_b128 v[154:157], v158 offset:2048
	ds_read_b128 v[158:161], v158 offset:3072
	ds_read_b128 v[162:165], v174
	ds_read_b128 v[166:169], v174 offset:1024
	ds_read_b128 v[170:173], v174 offset:2048
	ds_read_b128 v[174:177], v174 offset:3072
	s_add_u32 s40, s40, 0x40000
	s_addc_u32 s41, s41, 0
	s_mov_b32 m0, s53
	v_lshl_add_u64 v[238:239], s[40:41], 0, v[130:131]
	ds_read_b128 v[182:185], v211 offset:32768
	ds_read_b128 v[186:189], v211 offset:33792
	ds_read_b128 v[190:193], v211 offset:34816
	ds_read_b128 v[194:197], v211 offset:35840
	ds_read_b128 v[198:201], v211 offset:36864
	ds_read_b128 v[202:205], v211 offset:37888
	ds_read_b128 v[216:219], v211 offset:38912
	ds_read_b128 v[232:235], v211 offset:39936
	global_load_lds_dwordx4 v[238:239], off
	v_lshl_add_u64 v[238:239], s[40:41], 0, v[134:135]
	s_mov_b32 m0, s54
	s_nop 0
	global_load_lds_dwordx4 v[238:239], off
	s_waitcnt vmcnt(8)
	s_waitcnt lgkmcnt(0)
	s_barrier
	s_setprio 1
	v_mfma_f32_16x16x32_bf16 v[126:129], v[146:149], v[182:185], v[126:129]
	v_mfma_f32_16x16x32_bf16 v[110:113], v[146:149], v[190:193], v[110:113]
	v_mfma_f32_16x16x32_bf16 v[94:97], v[146:149], v[198:201], v[94:97]
	v_mfma_f32_16x16x32_bf16 v[78:81], v[146:149], v[216:219], v[78:81]
	v_mfma_f32_16x16x32_bf16 v[122:125], v[154:157], v[182:185], v[122:125]
	v_mfma_f32_16x16x32_bf16 v[106:109], v[154:157], v[190:193], v[106:109]
	v_mfma_f32_16x16x32_bf16 v[90:93], v[154:157], v[198:201], v[90:93]
	v_mfma_f32_16x16x32_bf16 v[74:77], v[154:157], v[216:219], v[74:77]
	v_mfma_f32_16x16x32_bf16 v[126:129], v[150:153], v[186:189], v[126:129]
	v_mfma_f32_16x16x32_bf16 v[110:113], v[150:153], v[194:197], v[110:113]
	v_mfma_f32_16x16x32_bf16 v[94:97], v[150:153], v[202:205], v[94:97]
	v_mfma_f32_16x16x32_bf16 v[78:81], v[150:153], v[232:235], v[78:81]
	v_mfma_f32_16x16x32_bf16 v[122:125], v[158:161], v[186:189], v[122:125]
	v_mfma_f32_16x16x32_bf16 v[106:109], v[158:161], v[194:197], v[106:109]
	v_mfma_f32_16x16x32_bf16 v[90:93], v[158:161], v[202:205], v[90:93]
	v_mfma_f32_16x16x32_bf16 v[74:77], v[158:161], v[232:235], v[74:77]
	v_mfma_f32_16x16x32_bf16 v[118:121], v[162:165], v[182:185], v[118:121]
	v_mfma_f32_16x16x32_bf16 v[102:105], v[162:165], v[190:193], v[102:105]
	v_mfma_f32_16x16x32_bf16 v[86:89], v[162:165], v[198:201], v[86:89]
	v_mfma_f32_16x16x32_bf16 v[70:73], v[162:165], v[216:219], v[70:73]
	v_mfma_f32_16x16x32_bf16 v[114:117], v[170:173], v[182:185], v[114:117]
	v_mfma_f32_16x16x32_bf16 v[98:101], v[170:173], v[190:193], v[98:101]
	v_mfma_f32_16x16x32_bf16 v[82:85], v[170:173], v[198:201], v[82:85]
	v_mfma_f32_16x16x32_bf16 v[66:69], v[170:173], v[216:219], v[66:69]
	v_mfma_f32_16x16x32_bf16 v[118:121], v[166:169], v[186:189], v[118:121]
	v_mfma_f32_16x16x32_bf16 v[102:105], v[166:169], v[194:197], v[102:105]
	v_mfma_f32_16x16x32_bf16 v[86:89], v[166:169], v[202:205], v[86:89]
	v_mfma_f32_16x16x32_bf16 v[70:73], v[166:169], v[232:235], v[70:73]
	v_mfma_f32_16x16x32_bf16 v[114:117], v[174:177], v[186:189], v[114:117]
	v_mfma_f32_16x16x32_bf16 v[98:101], v[174:177], v[194:197], v[98:101]
	v_mfma_f32_16x16x32_bf16 v[82:85], v[174:177], v[202:205], v[82:85]
	v_mfma_f32_16x16x32_bf16 v[66:69], v[174:177], v[232:235], v[66:69]
	s_setprio 0
	s_barrier
; #define PG8_STAGE(bufoff, gbase, voff) do { _Pragma("unroll") for (int _i = 0; _i < 2; ++_i) \
;         __builtin_amdgcn_global_load_lds((const unsigned*)((const char*)(gbase) + (voff)[_i]), (LAS unsigned*)(lds + (bufoff) + ldsw + _i * 8192), 16, 0, 0); } while (0)
; #define PG8_LDA(dst, b, h) do { _Pragma("unroll") for (int m = 0; m < 4; ++m) _Pragma("unroll") for (int k = 0; k < 2; ++k) dst[m][k] = *(const LAS bf16x8*)(lds + PG8_SA(b, h) + aoff + m * 2048 + k * 1024); } while (0)
; #define PG8_MMA(ai, bj, At, Bt) do { __builtin_amdgcn_s_setprio(1); _Pragma("unroll") for (int m = 0; m < 4; ++m) _Pragma("unroll") for (int n = 0; n < 2; ++n) _Pragma("unroll") for (int k = 0; k < 2; ++k) \
;         acc[ai][bj][m][n] = __builtin_amdgcn_mfma_f32_16x16x32_bf16(Bt[n][k], At[m][k], acc[ai][bj][m][n], 0, 0, 0); __builtin_amdgcn_s_setprio(0); } while (0)
; #define PG8_WAIT_V(n) asm volatile("s_waitcnt vmcnt(" #n ")" ::: "memory")
; #define PG8_WAIT_L(n) asm volatile("s_waitcnt lgkmcnt(" #n ")" ::: "memory")
; #define PG8_BAR __builtin_amdgcn_s_barrier()
; #define PG8_SCHED __builtin_amdgcn_sched_barrier(0)
; template <class Epi>
; __device__ __forceinline__ void gemm_phase(LAS unsigned char* lds, const Gemm g, const StaticOrder& S, const Epi& E) {
;     ...
;             PG8_LDA(At, 1, 1); PG8_STAGE(PG8_SB(1, 0), b3, voffB); PG8_STAGE(PG8_SB(1, 1), b3 + hB, voffB); PG8_STAGE(PG8_SA(1, 0), a3, voffA);
;             PG8_WAIT_V(8); PG8_WAIT_L(0); PG8_BAR; PG8_MMA(1, 0, At, B0); PG8_MMA(1, 1, At, B1); PG8_BAR; PG8_SCHED;
;         }
;         if (wr == 0) PG8_BAR;
	s_add_i32 s35, s35, s50
	v_lshl_add_u64 v[178:179], v[178:179], 0, s[88:89]
	s_mov_b32 m0, s35
	ds_read_b128 v[182:185], v211 offset:49152
	ds_read_b128 v[186:189], v211 offset:50176
	ds_read_b128 v[190:193], v211 offset:51200
	ds_read_b128 v[194:197], v211 offset:52224
	ds_read_b128 v[198:201], v211 offset:53248
	ds_read_b128 v[202:205], v211 offset:54272
	ds_read_b128 v[216:219], v211 offset:55296
	ds_read_b128 v[232:235], v211 offset:56320
	global_load_lds_dwordx4 v[178:179], off
	s_add_i32 m0, s35, 0x2000
	s_add_u32 s10, s10, 0x40080
	v_lshl_add_u64 v[178:179], v[206:207], 0, s[88:89]
	s_addc_u32 s11, s11, 0
	s_add_i32 s35, s42, s50
	global_load_lds_dwordx4 v[178:179], off
	v_lshl_add_u64 v[178:179], s[10:11], 0, v[132:133]
	s_mov_b32 m0, s35
	s_nop 0
	global_load_lds_dwordx4 v[178:179], off
	v_lshl_add_u64 v[178:179], s[10:11], 0, v[136:137]
	s_add_i32 m0, s35, 0x2000
	s_nop 0
	global_load_lds_dwordx4 v[178:179], off
	v_lshl_add_u64 v[178:179], v[220:221], 0, s[88:89]
	s_mov_b32 m0, s55
	s_nop 0
	global_load_lds_dwordx4 v[178:179], off
	v_lshl_add_u64 v[178:179], v[236:237], 0, s[88:89]
	s_mov_b32 m0, s56
	s_nop 0
	global_load_lds_dwordx4 v[178:179], off
	s_waitcnt vmcnt(8)
	s_waitcnt lgkmcnt(0)
	s_barrier
	s_setprio 1
	v_mfma_f32_16x16x32_bf16 v[62:65], v[146:149], v[182:185], v[62:65]
	v_mfma_f32_16x16x32_bf16 v[46:49], v[146:149], v[190:193], v[46:49]
	v_mfma_f32_16x16x32_bf16 v[30:33], v[146:149], v[198:201], v[30:33]
	v_mfma_f32_16x16x32_bf16 v[14:17], v[146:149], v[216:219], v[14:17]
	v_mfma_f32_16x16x32_bf16 v[58:61], v[154:157], v[182:185], v[58:61]
	v_mfma_f32_16x16x32_bf16 v[42:45], v[154:157], v[190:193], v[42:45]
	v_mfma_f32_16x16x32_bf16 v[26:29], v[154:157], v[198:201], v[26:29]
	v_mfma_f32_16x16x32_bf16 v[10:13], v[154:157], v[216:219], v[10:13]
	v_mfma_f32_16x16x32_bf16 v[62:65], v[150:153], v[186:189], v[62:65]
	v_mfma_f32_16x16x32_bf16 v[46:49], v[150:153], v[194:197], v[46:49]
	v_mfma_f32_16x16x32_bf16 v[30:33], v[150:153], v[202:205], v[30:33]
	v_mfma_f32_16x16x32_bf16 v[14:17], v[150:153], v[232:235], v[14:17]
	v_mfma_f32_16x16x32_bf16 v[58:61], v[158:161], v[186:189], v[58:61]
	v_mfma_f32_16x16x32_bf16 v[42:45], v[158:161], v[194:197], v[42:45]
	v_mfma_f32_16x16x32_bf16 v[26:29], v[158:161], v[202:205], v[26:29]
	v_mfma_f32_16x16x32_bf16 v[10:13], v[158:161], v[232:235], v[10:13]
	v_mfma_f32_16x16x32_bf16 v[54:57], v[162:165], v[182:185], v[54:57]
	v_mfma_f32_16x16x32_bf16 v[38:41], v[162:165], v[190:193], v[38:41]
	v_mfma_f32_16x16x32_bf16 v[22:25], v[162:165], v[198:201], v[22:25]
	v_mfma_f32_16x16x32_bf16 v[6:9], v[162:165], v[216:219], v[6:9]
	v_mfma_f32_16x16x32_bf16 v[50:53], v[170:173], v[182:185], v[50:53]
	v_mfma_f32_16x16x32_bf16 v[34:37], v[170:173], v[190:193], v[34:37]
	v_mfma_f32_16x16x32_bf16 v[18:21], v[170:173], v[198:201], v[18:21]
	v_mfma_f32_16x16x32_bf16 v[2:5], v[170:173], v[216:219], v[2:5]
	v_mfma_f32_16x16x32_bf16 v[54:57], v[166:169], v[186:189], v[54:57]
	v_mfma_f32_16x16x32_bf16 v[38:41], v[166:169], v[194:197], v[38:41]
	v_mfma_f32_16x16x32_bf16 v[22:25], v[166:169], v[202:205], v[22:25]
	v_mfma_f32_16x16x32_bf16 v[6:9], v[166:169], v[232:235], v[6:9]
	v_mfma_f32_16x16x32_bf16 v[50:53], v[174:177], v[186:189], v[50:53]
	v_mfma_f32_16x16x32_bf16 v[34:37], v[174:177], v[194:197], v[34:37]
	v_mfma_f32_16x16x32_bf16 v[18:21], v[174:177], v[202:205], v[18:21]
	v_mfma_f32_16x16x32_bf16 v[2:5], v[174:177], v[232:235], v[2:5]
	s_setprio 0
	s_barrier
	s_add_i32 s31, s31, 2
	s_add_u32 s8, s8, 0x100
	s_addc_u32 s9, s9, 0
	s_add_u32 s27, s27, 0x100
	s_addc_u32 s29, s29, 0
	s_cmp_gt_u32 s31, 13
	s_cbranch_scc0 .LBB0_1398
	s_and_b64 vcc, exec, s[16:17]
	s_cbranch_vccz .LBB0_1401
	s_barrier

; #define PG8_STAGE(bufoff, gbase, voff) do { _Pragma("unroll") for (int _i = 0; _i < 2; ++_i) \
;         __builtin_amdgcn_global_load_lds((const unsigned*)((const char*)(gbase) + (voff)[_i]), (LAS unsigned*)(lds + (bufoff) + ldsw + _i * 8192), 16, 0, 0); } while (0)
; #define PG8_LDA(dst, b, h) do { _Pragma("unroll") for (int m = 0; m < 4; ++m) _Pragma("unroll") for (int k = 0; k < 2; ++k) dst[m][k] = *(const LAS bf16x8*)(lds + PG8_SA(b, h) + aoff + m * 2048 + k * 1024); } while (0)
; #define PG8_LDB(dst, b, h) do { _Pragma("unroll") for (int n = 0; n < 2; ++n) _Pragma("unroll") for (int k = 0; k < 2; ++k) dst[n][k] = *(const LAS bf16x8*)(lds + PG8_SB(b, h) + boff + n * 2048 + k * 1024); } while (0)
; #define PG8_MMA(ai, bj, At, Bt) do { __builtin_amdgcn_s_setprio(1); _Pragma("unroll") for (int m = 0; m < 4; ++m) _Pragma("unroll") for (int n = 0; n < 2; ++n) _Pragma("unroll") for (int k = 0; k < 2; ++k) \
;         acc[ai][bj][m][n] = __builtin_amdgcn_mfma_f32_16x16x32_bf16(Bt[n][k], At[m][k], acc[ai][bj][m][n], 0, 0, 0); __builtin_amdgcn_s_setprio(0); } while (0)
; #define PG8_WAIT_V(n) asm volatile("s_waitcnt vmcnt(" #n ")" ::: "memory")
; #define PG8_WAIT_L(n) asm volatile("s_waitcnt lgkmcnt(" #n ")" ::: "memory")
; #define PG8_BAR __builtin_amdgcn_s_barrier()
; #define PG8_SCHED __builtin_amdgcn_sched_barrier(0)
; template <class Epi>
; __device__ __forceinline__ void gemm_phase(LAS unsigned char* lds, const Gemm g, const StaticOrder& S, const Epi& E) {
;     ...
;             PG8_LDB(B0, 0, 0); PG8_LDB(B1, 0, 1); PG8_SCHED; PG8_LDA(At, 0, 0); PG8_STAGE(PG8_SA(1, 1), a1 + hA, voffA);
;             PG8_WAIT_V(8); PG8_WAIT_L(0); PG8_BAR; PG8_MMA(0, 0, At, B0); PG8_MMA(0, 1, At, B1); PG8_BAR; PG8_SCHED;
;             PG8_LDA(At, 0, 1); PG8_STAGE(PG8_SB(0, 0), b2, voffB); PG8_STAGE(PG8_SB(0, 1), b2 + hB, voffB); PG8_STAGE(PG8_SA(0, 0), a2, voffA);
.LBB0_1550:
	s_add_u32 s22, s20, 0xfffc0080
	s_addc_u32 s23, s21, -1
	s_add_i32 s51, 0, 0x10000
	s_cmp_eq_u32 s50, 12
	s_cselect_b32 s25, s15, s23
	s_cselect_b32 s24, s46, s22
	v_add_u32_e32 v142, s51, v143
	s_cselect_b32 s23, s13, s49
	s_cselect_b32 s22, s47, s48
	s_add_i32 s54, 0, 0x14000
	ds_read_b128 v[148:151], v142
	ds_read_b128 v[152:155], v142 offset:1024
	ds_read_b128 v[156:159], v142 offset:2048
	ds_read_b128 v[160:163], v142 offset:3072
	v_add_u32_e32 v142, s54, v143
	ds_read_b128 v[164:167], v142
	ds_read_b128 v[168:171], v142 offset:1024
	ds_read_b128 v[172:175], v142 offset:2048
	ds_read_b128 v[176:179], v142 offset:3072
	v_lshl_add_u64 v[214:215], s[20:21], 0, v[138:139]
	s_add_i32 m0, s34, 0xc000
	ds_read_b128 v[182:185], v147
	ds_read_b128 v[186:189], v147 offset:1024
	ds_read_b128 v[190:193], v147 offset:2048
	ds_read_b128 v[194:197], v147 offset:3072
	ds_read_b128 v[198:201], v147 offset:4096
	ds_read_b128 v[202:205], v147 offset:5120
	ds_read_b128 v[206:209], v147 offset:6144
	ds_read_b128 v[210:213], v147 offset:7168
	global_load_lds_dwordx4 v[214:215], off
	v_lshl_add_u64 v[214:215], s[20:21], 0, v[140:141]
	s_add_i32 m0, s34, 0xe000
	s_nop 0
	global_load_lds_dwordx4 v[214:215], off
	s_waitcnt vmcnt(8)
	s_waitcnt lgkmcnt(0)
	s_barrier
	s_setprio 1
	v_mfma_f32_16x16x32_bf16 v[126:129], v[148:151], v[182:185], v[126:129]
	v_mfma_f32_16x16x32_bf16 v[110:113], v[148:151], v[190:193], v[110:113]
	v_mfma_f32_16x16x32_bf16 v[94:97], v[148:151], v[198:201], v[94:97]
	v_mfma_f32_16x16x32_bf16 v[78:81], v[148:151], v[206:209], v[78:81]
	v_mfma_f32_16x16x32_bf16 v[122:125], v[156:159], v[182:185], v[122:125]
	v_mfma_f32_16x16x32_bf16 v[106:109], v[156:159], v[190:193], v[106:109]
	v_mfma_f32_16x16x32_bf16 v[90:93], v[156:159], v[198:201], v[90:93]
	v_mfma_f32_16x16x32_bf16 v[74:77], v[156:159], v[206:209], v[74:77]
	v_mfma_f32_16x16x32_bf16 v[126:129], v[152:155], v[186:189], v[126:129]
	v_mfma_f32_16x16x32_bf16 v[110:113], v[152:155], v[194:197], v[110:113]
	v_mfma_f32_16x16x32_bf16 v[94:97], v[152:155], v[202:205], v[94:97]
	v_mfma_f32_16x16x32_bf16 v[78:81], v[152:155], v[210:213], v[78:81]
	v_mfma_f32_16x16x32_bf16 v[122:125], v[160:163], v[186:189], v[122:125]
	v_mfma_f32_16x16x32_bf16 v[106:109], v[160:163], v[194:197], v[106:109]
	v_mfma_f32_16x16x32_bf16 v[90:93], v[160:163], v[202:205], v[90:93]
	v_mfma_f32_16x16x32_bf16 v[74:77], v[160:163], v[210:213], v[74:77]
	v_mfma_f32_16x16x32_bf16 v[118:121], v[164:167], v[182:185], v[118:121]
	v_mfma_f32_16x16x32_bf16 v[102:105], v[164:167], v[190:193], v[102:105]
	v_mfma_f32_16x16x32_bf16 v[86:89], v[164:167], v[198:201], v[86:89]
	v_mfma_f32_16x16x32_bf16 v[70:73], v[164:167], v[206:209], v[70:73]
	v_mfma_f32_16x16x32_bf16 v[114:117], v[172:175], v[182:185], v[114:117]
	v_mfma_f32_16x16x32_bf16 v[98:101], v[172:175], v[190:193], v[98:101]
	v_mfma_f32_16x16x32_bf16 v[82:85], v[172:175], v[198:201], v[82:85]
	v_mfma_f32_16x16x32_bf16 v[66:69], v[172:175], v[206:209], v[66:69]
	v_mfma_f32_16x16x32_bf16 v[118:121], v[168:171], v[186:189], v[118:121]
	v_mfma_f32_16x16x32_bf16 v[102:105], v[168:171], v[194:197], v[102:105]
	v_mfma_f32_16x16x32_bf16 v[86:89], v[168:171], v[202:205], v[86:89]
	v_mfma_f32_16x16x32_bf16 v[70:73], v[168:171], v[210:213], v[70:73]
	v_mfma_f32_16x16x32_bf16 v[114:117], v[176:179], v[186:189], v[114:117]
	v_mfma_f32_16x16x32_bf16 v[98:101], v[176:179], v[194:197], v[98:101]
	v_mfma_f32_16x16x32_bf16 v[82:85], v[176:179], v[202:205], v[82:85]
	v_mfma_f32_16x16x32_bf16 v[66:69], v[176:179], v[210:213], v[66:69]
	s_setprio 0
	s_barrier
	s_add_i32 s51, s51, s31
	v_lshl_add_u64 v[214:215], s[22:23], 0, v[134:135]
	s_mov_b32 m0, s51
	ds_read_b128 v[182:185], v147 offset:16384
	ds_read_b128 v[186:189], v147 offset:17408
	ds_read_b128 v[190:193], v147 offset:18432
	ds_read_b128 v[194:197], v147 offset:19456
	ds_read_b128 v[198:201], v147 offset:20480
	ds_read_b128 v[202:205], v147 offset:21504
	ds_read_b128 v[206:209], v147 offset:22528
	ds_read_b128 v[210:213], v147 offset:23552
	global_load_lds_dwordx4 v[214:215], off
	s_add_i32 m0, s51, 0x2000
	s_add_u32 s52, s22, 0x40000
	v_lshl_add_u64 v[216:217], s[22:23], 0, v[130:131]
	s_addc_u32 s53, s23, 0
	s_add_i32 s51, s54, s31
	global_load_lds_dwordx4 v[216:217], off
	v_lshl_add_u64 v[218:219], s[52:53], 0, v[134:135]
	s_mov_b32 m0, s51
	v_lshl_add_u64 v[220:221], s[24:25], 0, v[132:133]
	global_load_lds_dwordx4 v[218:219], off
	v_lshl_add_u64 v[218:219], s[52:53], 0, v[130:131]
	s_add_i32 m0, s51, 0x2000
	s_nop 0
	global_load_lds_dwordx4 v[218:219], off
	v_lshl_add_u64 v[218:219], s[24:25], 0, v[136:137]
	s_mov_b32 m0, s34
	s_nop 0
	global_load_lds_dwordx4 v[218:219], off
	s_mov_b32 m0, s35
	s_nop 0
	global_load_lds_dwordx4 v[220:221], off
	s_waitcnt vmcnt(8)
	s_waitcnt lgkmcnt(0)
	s_barrier
; #define PG8_STAGE(bufoff, gbase, voff) do { _Pragma("unroll") for (int _i = 0; _i < 2; ++_i) \
;         __builtin_amdgcn_global_load_lds((const unsigned*)((const char*)(gbase) + (voff)[_i]), (LAS unsigned*)(lds + (bufoff) + ldsw + _i * 8192), 16, 0, 0); } while (0)
; #define PG8_LDA(dst, b, h) do { _Pragma("unroll") for (int m = 0; m < 4; ++m) _Pragma("unroll") for (int k = 0; k < 2; ++k) dst[m][k] = *(const LAS bf16x8*)(lds + PG8_SA(b, h) + aoff + m * 2048 + k * 1024); } while (0)
; #define PG8_LDB(dst, b, h) do { _Pragma("unroll") for (int n = 0; n < 2; ++n) _Pragma("unroll") for (int k = 0; k < 2; ++k) dst[n][k] = *(const LAS bf16x8*)(lds + PG8_SB(b, h) + boff + n * 2048 + k * 1024); } while (0)
; #define PG8_MMA(ai, bj, At, Bt) do { __builtin_amdgcn_s_setprio(1); _Pragma("unroll") for (int m = 0; m < 4; ++m) _Pragma("unroll") for (int n = 0; n < 2; ++n) _Pragma("unroll") for (int k = 0; k < 2; ++k) \
;         acc[ai][bj][m][n] = __builtin_amdgcn_mfma_f32_16x16x32_bf16(Bt[n][k], At[m][k], acc[ai][bj][m][n], 0, 0, 0); __builtin_amdgcn_s_setprio(0); } while (0)
; #define PG8_WAIT_V(n) asm volatile("s_waitcnt vmcnt(" #n ")" ::: "memory")
; #define PG8_WAIT_L(n) asm volatile("s_waitcnt lgkmcnt(" #n ")" ::: "memory")
; #define PG8_BAR __builtin_amdgcn_s_barrier()
; #define PG8_SCHED __builtin_amdgcn_sched_barrier(0)
; template <class Epi>
; __device__ __forceinline__ void gemm_phase(LAS unsigned char* lds, const Gemm g, const StaticOrder& S, const Epi& E) {
;     ...
;             PG8_WAIT_V(8); PG8_WAIT_L(0); PG8_BAR; PG8_MMA(1, 0, At, B0); PG8_MMA(1, 1, At, B1); PG8_BAR; PG8_SCHED;
;             PG8_LDB(B0, 1, 0); PG8_LDB(B1, 1, 1); PG8_SCHED; PG8_LDA(At, 1, 0); PG8_STAGE(PG8_SA(0, 1), a2 + hA, voffA);
;             PG8_WAIT_V(8); PG8_WAIT_L(0); PG8_BAR; PG8_MMA(0, 0, At, B0); PG8_MMA(0, 1, At, B1); PG8_BAR; PG8_SCHED;
	s_setprio 1
	v_mfma_f32_16x16x32_bf16 v[62:65], v[148:151], v[182:185], v[62:65]
	v_mfma_f32_16x16x32_bf16 v[46:49], v[148:151], v[190:193], v[46:49]
	v_mfma_f32_16x16x32_bf16 v[30:33], v[148:151], v[198:201], v[30:33]
	v_mfma_f32_16x16x32_bf16 v[14:17], v[148:151], v[206:209], v[14:17]
	v_mfma_f32_16x16x32_bf16 v[58:61], v[156:159], v[182:185], v[58:61]
	v_mfma_f32_16x16x32_bf16 v[42:45], v[156:159], v[190:193], v[42:45]
	v_mfma_f32_16x16x32_bf16 v[26:29], v[156:159], v[198:201], v[26:29]
	v_mfma_f32_16x16x32_bf16 v[10:13], v[156:159], v[206:209], v[10:13]
	v_mfma_f32_16x16x32_bf16 v[62:65], v[152:155], v[186:189], v[62:65]
	v_mfma_f32_16x16x32_bf16 v[46:49], v[152:155], v[194:197], v[46:49]
	v_mfma_f32_16x16x32_bf16 v[30:33], v[152:155], v[202:205], v[30:33]
	v_mfma_f32_16x16x32_bf16 v[14:17], v[152:155], v[210:213], v[14:17]
	v_mfma_f32_16x16x32_bf16 v[58:61], v[160:163], v[186:189], v[58:61]
	v_mfma_f32_16x16x32_bf16 v[42:45], v[160:163], v[194:197], v[42:45]
	v_mfma_f32_16x16x32_bf16 v[26:29], v[160:163], v[202:205], v[26:29]
	v_mfma_f32_16x16x32_bf16 v[10:13], v[160:163], v[210:213], v[10:13]
	v_mfma_f32_16x16x32_bf16 v[54:57], v[164:167], v[182:185], v[54:57]
	v_mfma_f32_16x16x32_bf16 v[38:41], v[164:167], v[190:193], v[38:41]
	v_mfma_f32_16x16x32_bf16 v[22:25], v[164:167], v[198:201], v[22:25]
	v_mfma_f32_16x16x32_bf16 v[6:9], v[164:167], v[206:209], v[6:9]
	v_mfma_f32_16x16x32_bf16 v[50:53], v[172:175], v[182:185], v[50:53]
	v_mfma_f32_16x16x32_bf16 v[34:37], v[172:175], v[190:193], v[34:37]
	v_mfma_f32_16x16x32_bf16 v[18:21], v[172:175], v[198:201], v[18:21]
	v_mfma_f32_16x16x32_bf16 v[2:5], v[172:175], v[206:209], v[2:5]
	v_mfma_f32_16x16x32_bf16 v[54:57], v[168:171], v[186:189], v[54:57]
	v_mfma_f32_16x16x32_bf16 v[38:41], v[168:171], v[194:197], v[38:41]
	v_mfma_f32_16x16x32_bf16 v[22:25], v[168:171], v[202:205], v[22:25]
	v_mfma_f32_16x16x32_bf16 v[6:9], v[168:171], v[210:213], v[6:9]
	v_mfma_f32_16x16x32_bf16 v[50:53], v[176:179], v[186:189], v[50:53]
	v_mfma_f32_16x16x32_bf16 v[34:37], v[176:179], v[194:197], v[34:37]
	v_mfma_f32_16x16x32_bf16 v[18:21], v[176:179], v[202:205], v[18:21]
	v_mfma_f32_16x16x32_bf16 v[2:5], v[176:179], v[210:213], v[2:5]
	s_setprio 0
	s_barrier
	s_add_i32 s51, 0, 0x18000
	v_add_u32_e32 v142, s51, v143
	s_add_i32 s52, 0, 0x1c000
	ds_read_b128 v[148:151], v142
	ds_read_b128 v[152:155], v142 offset:1024
	ds_read_b128 v[156:159], v142 offset:2048
	ds_read_b128 v[160:163], v142 offset:3072
	v_add_u32_e32 v142, s52, v143
	ds_read_b128 v[164:167], v142
	ds_read_b128 v[168:171], v142 offset:1024
	ds_read_b128 v[172:175], v142 offset:2048
	ds_read_b128 v[176:179], v142 offset:3072
	s_add_u32 s24, s24, 0x40000
	s_addc_u32 s25, s25, 0
	s_mov_b32 m0, s36
	v_lshl_add_u64 v[232:233], s[24:25], 0, v[136:137]
	ds_read_b128 v[182:185], v147 offset:32768
	ds_read_b128 v[186:189], v147 offset:33792
	ds_read_b128 v[190:193], v147 offset:34816
	ds_read_b128 v[194:197], v147 offset:35840
	ds_read_b128 v[198:201], v147 offset:36864
	ds_read_b128 v[202:205], v147 offset:37888
	ds_read_b128 v[206:209], v147 offset:38912
	ds_read_b128 v[210:213], v147 offset:39936
	global_load_lds_dwordx4 v[232:233], off
	v_lshl_add_u64 v[232:233], s[24:25], 0, v[132:133]
	s_mov_b32 m0, s37
	s_nop 0
	global_load_lds_dwordx4 v[232:233], off
	s_waitcnt vmcnt(8)
	s_waitcnt lgkmcnt(0)
	s_barrier
	s_setprio 1
	v_mfma_f32_16x16x32_bf16 v[126:129], v[148:151], v[182:185], v[126:129]
	v_mfma_f32_16x16x32_bf16 v[110:113], v[148:151], v[190:193], v[110:113]
	v_mfma_f32_16x16x32_bf16 v[94:97], v[148:151], v[198:201], v[94:97]
	v_mfma_f32_16x16x32_bf16 v[78:81], v[148:151], v[206:209], v[78:81]
	v_mfma_f32_16x16x32_bf16 v[122:125], v[156:159], v[182:185], v[122:125]
	v_mfma_f32_16x16x32_bf16 v[106:109], v[156:159], v[190:193], v[106:109]
	v_mfma_f32_16x16x32_bf16 v[90:93], v[156:159], v[198:201], v[90:93]
	v_mfma_f32_16x16x32_bf16 v[74:77], v[156:159], v[206:209], v[74:77]
	v_mfma_f32_16x16x32_bf16 v[126:129], v[152:155], v[186:189], v[126:129]
	v_mfma_f32_16x16x32_bf16 v[110:113], v[152:155], v[194:197], v[110:113]
	v_mfma_f32_16x16x32_bf16 v[94:97], v[152:155], v[202:205], v[94:97]
	v_mfma_f32_16x16x32_bf16 v[78:81], v[152:155], v[210:213], v[78:81]
	v_mfma_f32_16x16x32_bf16 v[122:125], v[160:163], v[186:189], v[122:125]
	v_mfma_f32_16x16x32_bf16 v[106:109], v[160:163], v[194:197], v[106:109]
	v_mfma_f32_16x16x32_bf16 v[90:93], v[160:163], v[202:205], v[90:93]
	v_mfma_f32_16x16x32_bf16 v[74:77], v[160:163], v[210:213], v[74:77]
	v_mfma_f32_16x16x32_bf16 v[118:121], v[164:167], v[182:185], v[118:121]
	v_mfma_f32_16x16x32_bf16 v[102:105], v[164:167], v[190:193], v[102:105]
	v_mfma_f32_16x16x32_bf16 v[86:89], v[164:167], v[198:201], v[86:89]
	v_mfma_f32_16x16x32_bf16 v[70:73], v[164:167], v[206:209], v[70:73]
	v_mfma_f32_16x16x32_bf16 v[114:117], v[172:175], v[182:185], v[114:117]
	v_mfma_f32_16x16x32_bf16 v[98:101], v[172:175], v[190:193], v[98:101]
	v_mfma_f32_16x16x32_bf16 v[82:85], v[172:175], v[198:201], v[82:85]
	v_mfma_f32_16x16x32_bf16 v[66:69], v[172:175], v[206:209], v[66:69]
	v_mfma_f32_16x16x32_bf16 v[118:121], v[168:171], v[186:189], v[118:121]
	v_mfma_f32_16x16x32_bf16 v[102:105], v[168:171], v[194:197], v[102:105]
	v_mfma_f32_16x16x32_bf16 v[86:89], v[168:171], v[202:205], v[86:89]
	v_mfma_f32_16x16x32_bf16 v[70:73], v[168:171], v[210:213], v[70:73]
	v_mfma_f32_16x16x32_bf16 v[114:117], v[176:179], v[186:189], v[114:117]
	v_mfma_f32_16x16x32_bf16 v[98:101], v[176:179], v[194:197], v[98:101]
	v_mfma_f32_16x16x32_bf16 v[82:85], v[176:179], v[202:205], v[82:85]
	v_mfma_f32_16x16x32_bf16 v[66:69], v[176:179], v[210:213], v[66:69]
	s_setprio 0
	s_barrier
; #define PG8_STAGE(bufoff, gbase, voff) do { _Pragma("unroll") for (int _i = 0; _i < 2; ++_i) \
;         __builtin_amdgcn_global_load_lds((const unsigned*)((const char*)(gbase) + (voff)[_i]), (LAS unsigned*)(lds + (bufoff) + ldsw + _i * 8192), 16, 0, 0); } while (0)
; #define PG8_LDA(dst, b, h) do { _Pragma("unroll") for (int m = 0; m < 4; ++m) _Pragma("unroll") for (int k = 0; k < 2; ++k) dst[m][k] = *(const LAS bf16x8*)(lds + PG8_SA(b, h) + aoff + m * 2048 + k * 1024); } while (0)
; #define PG8_MMA(ai, bj, At, Bt) do { __builtin_amdgcn_s_setprio(1); _Pragma("unroll") for (int m = 0; m < 4; ++m) _Pragma("unroll") for (int n = 0; n < 2; ++n) _Pragma("unroll") for (int k = 0; k < 2; ++k) \
;         acc[ai][bj][m][n] = __builtin_amdgcn_mfma_f32_16x16x32_bf16(Bt[n][k], At[m][k], acc[ai][bj][m][n], 0, 0, 0); __builtin_amdgcn_s_setprio(0); } while (0)
; #define PG8_WAIT_V(n) asm volatile("s_waitcnt vmcnt(" #n ")" ::: "memory")
; #define PG8_WAIT_L(n) asm volatile("s_waitcnt lgkmcnt(" #n ")" ::: "memory")
; #define PG8_BAR __builtin_amdgcn_s_barrier()
; #define PG8_SCHED __builtin_amdgcn_sched_barrier(0)
; template <class Epi>
; __device__ __forceinline__ void gemm_phase(LAS unsigned char* lds, const Gemm g, const StaticOrder& S, const Epi& E) {
;     ...
;             PG8_LDA(At, 1, 1); PG8_STAGE(PG8_SB(1, 0), b3, voffB); PG8_STAGE(PG8_SB(1, 1), b3 + hB, voffB); PG8_STAGE(PG8_SA(1, 0), a3, voffA);
;             PG8_WAIT_V(8); PG8_WAIT_L(0); PG8_BAR; PG8_MMA(1, 0, At, B0); PG8_MMA(1, 1, At, B1); PG8_BAR; PG8_SCHED;
;         }
;         if (wr == 0) PG8_BAR;
	s_add_i32 s24, s51, s31
	v_lshl_add_u64 v[214:215], v[214:215], 0, s[88:89]
	s_mov_b32 m0, s24
	ds_read_b128 v[182:185], v147 offset:49152
	ds_read_b128 v[186:189], v147 offset:50176
	ds_read_b128 v[190:193], v147 offset:51200
	ds_read_b128 v[194:197], v147 offset:52224
	ds_read_b128 v[198:201], v147 offset:53248
	ds_read_b128 v[202:205], v147 offset:54272
	ds_read_b128 v[206:209], v147 offset:55296
	ds_read_b128 v[210:213], v147 offset:56320
	global_load_lds_dwordx4 v[214:215], off
	s_add_i32 m0, s24, 0x2000
	s_add_u32 s22, s22, 0x40080
	v_lshl_add_u64 v[214:215], v[216:217], 0, s[88:89]
	s_addc_u32 s23, s23, 0
	s_add_i32 s24, s52, s31
	global_load_lds_dwordx4 v[214:215], off
	v_lshl_add_u64 v[214:215], s[22:23], 0, v[134:135]
	s_mov_b32 m0, s24
	s_nop 0
	global_load_lds_dwordx4 v[214:215], off
	v_lshl_add_u64 v[214:215], s[22:23], 0, v[130:131]
	s_add_i32 m0, s24, 0x2000
	s_nop 0
	global_load_lds_dwordx4 v[214:215], off
	v_lshl_add_u64 v[214:215], v[218:219], 0, s[88:89]
	s_mov_b32 m0, s38
	s_nop 0
	global_load_lds_dwordx4 v[214:215], off
	v_lshl_add_u64 v[214:215], v[220:221], 0, s[88:89]
	s_mov_b32 m0, s39
	s_nop 0
	global_load_lds_dwordx4 v[214:215], off
	s_waitcnt vmcnt(8)
	s_waitcnt lgkmcnt(0)
	s_barrier
	s_setprio 1
	v_mfma_f32_16x16x32_bf16 v[62:65], v[148:151], v[182:185], v[62:65]
	v_mfma_f32_16x16x32_bf16 v[46:49], v[148:151], v[190:193], v[46:49]
	v_mfma_f32_16x16x32_bf16 v[30:33], v[148:151], v[198:201], v[30:33]
	v_mfma_f32_16x16x32_bf16 v[14:17], v[148:151], v[206:209], v[14:17]
	v_mfma_f32_16x16x32_bf16 v[58:61], v[156:159], v[182:185], v[58:61]
	v_mfma_f32_16x16x32_bf16 v[42:45], v[156:159], v[190:193], v[42:45]
	v_mfma_f32_16x16x32_bf16 v[26:29], v[156:159], v[198:201], v[26:29]
	v_mfma_f32_16x16x32_bf16 v[10:13], v[156:159], v[206:209], v[10:13]
	v_mfma_f32_16x16x32_bf16 v[62:65], v[152:155], v[186:189], v[62:65]
	v_mfma_f32_16x16x32_bf16 v[46:49], v[152:155], v[194:197], v[46:49]
	v_mfma_f32_16x16x32_bf16 v[30:33], v[152:155], v[202:205], v[30:33]
	v_mfma_f32_16x16x32_bf16 v[14:17], v[152:155], v[210:213], v[14:17]
	v_mfma_f32_16x16x32_bf16 v[58:61], v[160:163], v[186:189], v[58:61]
	v_mfma_f32_16x16x32_bf16 v[42:45], v[160:163], v[194:197], v[42:45]
	v_mfma_f32_16x16x32_bf16 v[26:29], v[160:163], v[202:205], v[26:29]
	v_mfma_f32_16x16x32_bf16 v[10:13], v[160:163], v[210:213], v[10:13]
	v_mfma_f32_16x16x32_bf16 v[54:57], v[164:167], v[182:185], v[54:57]
	v_mfma_f32_16x16x32_bf16 v[38:41], v[164:167], v[190:193], v[38:41]
	v_mfma_f32_16x16x32_bf16 v[22:25], v[164:167], v[198:201], v[22:25]
	v_mfma_f32_16x16x32_bf16 v[6:9], v[164:167], v[206:209], v[6:9]
	v_mfma_f32_16x16x32_bf16 v[50:53], v[172:175], v[182:185], v[50:53]
	v_mfma_f32_16x16x32_bf16 v[34:37], v[172:175], v[190:193], v[34:37]
	v_mfma_f32_16x16x32_bf16 v[18:21], v[172:175], v[198:201], v[18:21]
	v_mfma_f32_16x16x32_bf16 v[2:5], v[172:175], v[206:209], v[2:5]
	v_mfma_f32_16x16x32_bf16 v[54:57], v[168:171], v[186:189], v[54:57]
	v_mfma_f32_16x16x32_bf16 v[38:41], v[168:171], v[194:197], v[38:41]
	v_mfma_f32_16x16x32_bf16 v[22:25], v[168:171], v[202:205], v[22:25]
	v_mfma_f32_16x16x32_bf16 v[6:9], v[168:171], v[210:213], v[6:9]
	v_mfma_f32_16x16x32_bf16 v[50:53], v[176:179], v[186:189], v[50:53]
	v_mfma_f32_16x16x32_bf16 v[34:37], v[176:179], v[194:197], v[34:37]
	v_mfma_f32_16x16x32_bf16 v[18:21], v[176:179], v[202:205], v[18:21]
	v_mfma_f32_16x16x32_bf16 v[2:5], v[176:179], v[210:213], v[2:5]
	s_setprio 0
	s_barrier
	s_add_i32 s50, s50, 2
	s_add_u32 s20, s20, 0x100
	s_addc_u32 s21, s21, 0
	s_add_u32 s48, s48, 0x100
	s_addc_u32 s49, s49, 0
	s_cmp_gt_u32 s50, 13
	s_cbranch_scc0 .LBB0_1550
	s_and_b64 vcc, exec, s[10:11]
	s_cbranch_vccz .LBB0_1553
	s_barrier

; #define PG8_STAGE(bufoff, gbase, voff) do { _Pragma("unroll") for (int _i = 0; _i < 2; ++_i) \
;         __builtin_amdgcn_global_load_lds((const unsigned*)((const char*)(gbase) + (voff)[_i]), (LAS unsigned*)(lds + (bufoff) + ldsw + _i * 8192), 16, 0, 0); } while (0)
; #define PG8_LDA(dst, b, h) do { _Pragma("unroll") for (int m = 0; m < 4; ++m) _Pragma("unroll") for (int k = 0; k < 2; ++k) dst[m][k] = *(const LAS bf16x8*)(lds + PG8_SA(b, h) + aoff + m * 2048 + k * 1024); } while (0)
; #define PG8_LDB(dst, b, h) do { _Pragma("unroll") for (int n = 0; n < 2; ++n) _Pragma("unroll") for (int k = 0; k < 2; ++k) dst[n][k] = *(const LAS bf16x8*)(lds + PG8_SB(b, h) + boff + n * 2048 + k * 1024); } while (0)
; #define PG8_MMA(ai, bj, At, Bt) do { __builtin_amdgcn_s_setprio(1); _Pragma("unroll") for (int m = 0; m < 4; ++m) _Pragma("unroll") for (int n = 0; n < 2; ++n) _Pragma("unroll") for (int k = 0; k < 2; ++k) \
;         acc[ai][bj][m][n] = __builtin_amdgcn_mfma_f32_16x16x32_bf16(Bt[n][k], At[m][k], acc[ai][bj][m][n], 0, 0, 0); __builtin_amdgcn_s_setprio(0); } while (0)
; #define PG8_WAIT_V(n) asm volatile("s_waitcnt vmcnt(" #n ")" ::: "memory")
; #define PG8_WAIT_L(n) asm volatile("s_waitcnt lgkmcnt(" #n ")" ::: "memory")
; #define PG8_BAR __builtin_amdgcn_s_barrier()
; #define PG8_SCHED __builtin_amdgcn_sched_barrier(0)
; template <class Epi>
; __device__ __forceinline__ void gemm_phase(LAS unsigned char* lds, const Gemm g, const StaticOrder& S, const Epi& E) {
;     ...
;             PG8_LDB(B0, 0, 0); PG8_LDB(B1, 0, 1); PG8_SCHED; PG8_LDA(At, 0, 0); PG8_STAGE(PG8_SA(1, 1), a1 + hA, voffA);
;             PG8_WAIT_V(8); PG8_WAIT_L(0); PG8_BAR; PG8_MMA(0, 0, At, B0); PG8_MMA(0, 1, At, B1); PG8_BAR; PG8_SCHED;
;             PG8_LDA(At, 0, 1); PG8_STAGE(PG8_SB(0, 0), b2, voffB); PG8_STAGE(PG8_SB(0, 1), b2 + hB, voffB); PG8_STAGE(PG8_SA(0, 0), a2, voffA);
.LBB0_1632:
	s_add_u32 s8, s10, 0x100
	s_addc_u32 s9, s11, 0
	s_add_i32 s70, 0, 0x10000
	s_cmp_eq_u32 s67, 40
	s_cselect_b32 s45, s39, s9
	s_cselect_b32 s44, s38, s8
	s_cselect_b32 s43, s41, s37
	s_cselect_b32 s42, s40, s35
	s_add_i32 s71, 0, 0x14000
	s_waitcnt lgkmcnt(0)
	v_add_u32_e32 v158, s70, v180
	v_add_u32_e32 v174, s71, v180
	ds_read_b128 v[146:149], v158
	ds_read_b128 v[150:153], v158 offset:1024
	ds_read_b128 v[154:157], v158 offset:2048
	ds_read_b128 v[158:161], v158 offset:3072
	ds_read_b128 v[162:165], v174
	ds_read_b128 v[166:169], v174 offset:1024
	ds_read_b128 v[170:173], v174 offset:2048
	ds_read_b128 v[174:177], v174 offset:3072
	v_lshl_add_u64 v[178:179], s[10:11], 0, v[142:143]
	s_add_i32 m0, s52, 0xc000
	ds_read_b128 v[182:185], v192
	ds_read_b128 v[196:199], v192 offset:1024
	ds_read_b128 v[200:203], v192 offset:2048
	ds_read_b128 v[204:207], v192 offset:3072
	ds_read_b128 v[208:211], v192 offset:4096
	ds_read_b128 v[212:215], v192 offset:5120
	ds_read_b128 v[216:219], v192 offset:6144
	ds_read_b128 v[232:235], v192 offset:7168
	global_load_lds_dwordx4 v[178:179], off
	v_lshl_add_u64 v[178:179], s[10:11], 0, v[144:145]
	s_add_i32 m0, s52, 0xe000
	s_nop 0
	global_load_lds_dwordx4 v[178:179], off
	s_waitcnt vmcnt(8)
	s_waitcnt lgkmcnt(0)
	s_barrier
	s_setprio 1
	v_mfma_f32_16x16x32_bf16 v[26:29], v[146:149], v[182:185], v[26:29]
	v_mfma_f32_16x16x32_bf16 v[58:61], v[146:149], v[200:203], v[58:61]
	v_mfma_f32_16x16x32_bf16 v[90:93], v[146:149], v[208:211], v[90:93]
	v_mfma_f32_16x16x32_bf16 v[114:117], v[146:149], v[216:219], v[114:117]
	v_mfma_f32_16x16x32_bf16 v[30:33], v[154:157], v[182:185], v[30:33]
	v_mfma_f32_16x16x32_bf16 v[62:65], v[154:157], v[200:203], v[62:65]
	v_mfma_f32_16x16x32_bf16 v[94:97], v[154:157], v[208:211], v[94:97]
	v_mfma_f32_16x16x32_bf16 v[118:121], v[154:157], v[216:219], v[118:121]
	v_mfma_f32_16x16x32_bf16 v[26:29], v[150:153], v[196:199], v[26:29]
	v_mfma_f32_16x16x32_bf16 v[58:61], v[150:153], v[204:207], v[58:61]
	v_mfma_f32_16x16x32_bf16 v[90:93], v[150:153], v[212:215], v[90:93]
	v_mfma_f32_16x16x32_bf16 v[114:117], v[150:153], v[232:235], v[114:117]
	v_mfma_f32_16x16x32_bf16 v[30:33], v[158:161], v[196:199], v[30:33]
	v_mfma_f32_16x16x32_bf16 v[62:65], v[158:161], v[204:207], v[62:65]
	v_mfma_f32_16x16x32_bf16 v[94:97], v[158:161], v[212:215], v[94:97]
	v_mfma_f32_16x16x32_bf16 v[118:121], v[158:161], v[232:235], v[118:121]
	v_mfma_f32_16x16x32_bf16 v[42:45], v[162:165], v[182:185], v[42:45]
	v_mfma_f32_16x16x32_bf16 v[74:77], v[162:165], v[200:203], v[74:77]
	v_mfma_f32_16x16x32_bf16 v[106:109], v[162:165], v[208:211], v[106:109]
	v_mfma_f32_16x16x32_bf16 v[126:129], v[162:165], v[216:219], v[126:129]
	v_mfma_f32_16x16x32_bf16 v[46:49], v[170:173], v[182:185], v[46:49]
	v_mfma_f32_16x16x32_bf16 v[78:81], v[170:173], v[200:203], v[78:81]
	v_mfma_f32_16x16x32_bf16 v[110:113], v[170:173], v[208:211], v[110:113]
	v_mfma_f32_16x16x32_bf16 v[122:125], v[170:173], v[216:219], v[122:125]
	v_mfma_f32_16x16x32_bf16 v[42:45], v[166:169], v[196:199], v[42:45]
	v_mfma_f32_16x16x32_bf16 v[74:77], v[166:169], v[204:207], v[74:77]
	v_mfma_f32_16x16x32_bf16 v[106:109], v[166:169], v[212:215], v[106:109]
	v_mfma_f32_16x16x32_bf16 v[126:129], v[166:169], v[232:235], v[126:129]
	v_mfma_f32_16x16x32_bf16 v[46:49], v[174:177], v[196:199], v[46:49]
	v_mfma_f32_16x16x32_bf16 v[78:81], v[174:177], v[204:207], v[78:81]
	v_mfma_f32_16x16x32_bf16 v[110:113], v[174:177], v[212:215], v[110:113]
	v_mfma_f32_16x16x32_bf16 v[122:125], v[174:177], v[232:235], v[122:125]
	s_setprio 0
	s_barrier
	s_add_i32 s10, s70, s47
	v_lshl_add_u64 v[178:179], s[42:43], 0, v[132:133]
	s_mov_b32 m0, s10
	ds_read_b128 v[182:185], v192 offset:16384
	ds_read_b128 v[196:199], v192 offset:17408
	ds_read_b128 v[200:203], v192 offset:18432
	ds_read_b128 v[204:207], v192 offset:19456
	ds_read_b128 v[208:211], v192 offset:20480
	ds_read_b128 v[212:215], v192 offset:21504
	ds_read_b128 v[216:219], v192 offset:22528
	ds_read_b128 v[232:235], v192 offset:23552
	global_load_lds_dwordx4 v[178:179], off
	s_add_i32 m0, s10, 0x2000
	s_add_u32 s10, s42, 0xb0000
	v_lshl_add_u64 v[186:187], s[42:43], 0, v[136:137]
	s_addc_u32 s11, s43, 0
	s_add_i32 s70, s71, s47
	global_load_lds_dwordx4 v[186:187], off
	v_lshl_add_u64 v[220:221], s[10:11], 0, v[132:133]
	s_mov_b32 m0, s70
	v_lshl_add_u64 v[236:237], s[44:45], 0, v[134:135]
	global_load_lds_dwordx4 v[220:221], off
	v_lshl_add_u64 v[220:221], s[10:11], 0, v[136:137]
	s_add_i32 m0, s70, 0x2000
	s_nop 0
	global_load_lds_dwordx4 v[220:221], off
	v_lshl_add_u64 v[220:221], s[44:45], 0, v[130:131]
	s_mov_b32 m0, s52
	s_nop 0
	global_load_lds_dwordx4 v[220:221], off
	s_mov_b32 m0, s53
	s_nop 0
	global_load_lds_dwordx4 v[236:237], off
	s_waitcnt vmcnt(8)
	s_waitcnt lgkmcnt(0)
	s_barrier
; #define PG8_STAGE(bufoff, gbase, voff) do { _Pragma("unroll") for (int _i = 0; _i < 2; ++_i) \
;         __builtin_amdgcn_global_load_lds((const unsigned*)((const char*)(gbase) + (voff)[_i]), (LAS unsigned*)(lds + (bufoff) + ldsw + _i * 8192), 16, 0, 0); } while (0)
; #define PG8_LDA(dst, b, h) do { _Pragma("unroll") for (int m = 0; m < 4; ++m) _Pragma("unroll") for (int k = 0; k < 2; ++k) dst[m][k] = *(const LAS bf16x8*)(lds + PG8_SA(b, h) + aoff + m * 2048 + k * 1024); } while (0)
; #define PG8_LDB(dst, b, h) do { _Pragma("unroll") for (int n = 0; n < 2; ++n) _Pragma("unroll") for (int k = 0; k < 2; ++k) dst[n][k] = *(const LAS bf16x8*)(lds + PG8_SB(b, h) + boff + n * 2048 + k * 1024); } while (0)
; #define PG8_MMA(ai, bj, At, Bt) do { __builtin_amdgcn_s_setprio(1); _Pragma("unroll") for (int m = 0; m < 4; ++m) _Pragma("unroll") for (int n = 0; n < 2; ++n) _Pragma("unroll") for (int k = 0; k < 2; ++k) \
;         acc[ai][bj][m][n] = __builtin_amdgcn_mfma_f32_16x16x32_bf16(Bt[n][k], At[m][k], acc[ai][bj][m][n], 0, 0, 0); __builtin_amdgcn_s_setprio(0); } while (0)
; #define PG8_WAIT_V(n) asm volatile("s_waitcnt vmcnt(" #n ")" ::: "memory")
; #define PG8_WAIT_L(n) asm volatile("s_waitcnt lgkmcnt(" #n ")" ::: "memory")
; #define PG8_BAR __builtin_amdgcn_s_barrier()
; #define PG8_SCHED __builtin_amdgcn_sched_barrier(0)
; template <class Epi>
; __device__ __forceinline__ void gemm_phase(LAS unsigned char* lds, const Gemm g, const StaticOrder& S, const Epi& E) {
;     ...
;             PG8_WAIT_V(8); PG8_WAIT_L(0); PG8_BAR; PG8_MMA(1, 0, At, B0); PG8_MMA(1, 1, At, B1); PG8_BAR; PG8_SCHED;
;             PG8_LDB(B0, 1, 0); PG8_LDB(B1, 1, 1); PG8_SCHED; PG8_LDA(At, 1, 0); PG8_STAGE(PG8_SA(0, 1), a2 + hA, voffA);
;             PG8_WAIT_V(8); PG8_WAIT_L(0); PG8_BAR; PG8_MMA(0, 0, At, B0); PG8_MMA(0, 1, At, B1); PG8_BAR; PG8_SCHED;
	s_setprio 1
	v_mfma_f32_16x16x32_bf16 v[102:105], v[146:149], v[182:185], v[102:105]
	v_mfma_f32_16x16x32_bf16 v[70:73], v[146:149], v[200:203], v[70:73]
	v_mfma_f32_16x16x32_bf16 v[38:41], v[146:149], v[208:211], v[38:41]
	v_mfma_f32_16x16x32_bf16 v[14:17], v[146:149], v[216:219], v[14:17]
	v_mfma_f32_16x16x32_bf16 v[98:101], v[154:157], v[182:185], v[98:101]
	v_mfma_f32_16x16x32_bf16 v[66:69], v[154:157], v[200:203], v[66:69]
	v_mfma_f32_16x16x32_bf16 v[34:37], v[154:157], v[208:211], v[34:37]
	v_mfma_f32_16x16x32_bf16 v[10:13], v[154:157], v[216:219], v[10:13]
	v_mfma_f32_16x16x32_bf16 v[102:105], v[150:153], v[196:199], v[102:105]
	v_mfma_f32_16x16x32_bf16 v[70:73], v[150:153], v[204:207], v[70:73]
	v_mfma_f32_16x16x32_bf16 v[38:41], v[150:153], v[212:215], v[38:41]
	v_mfma_f32_16x16x32_bf16 v[14:17], v[150:153], v[232:235], v[14:17]
	v_mfma_f32_16x16x32_bf16 v[98:101], v[158:161], v[196:199], v[98:101]
	v_mfma_f32_16x16x32_bf16 v[66:69], v[158:161], v[204:207], v[66:69]
	v_mfma_f32_16x16x32_bf16 v[34:37], v[158:161], v[212:215], v[34:37]
	v_mfma_f32_16x16x32_bf16 v[10:13], v[158:161], v[232:235], v[10:13]
	v_mfma_f32_16x16x32_bf16 v[86:89], v[162:165], v[182:185], v[86:89]
	v_mfma_f32_16x16x32_bf16 v[54:57], v[162:165], v[200:203], v[54:57]
	v_mfma_f32_16x16x32_bf16 v[22:25], v[162:165], v[208:211], v[22:25]
	v_mfma_f32_16x16x32_bf16 v[6:9], v[162:165], v[216:219], v[6:9]
	v_mfma_f32_16x16x32_bf16 v[82:85], v[170:173], v[182:185], v[82:85]
	v_mfma_f32_16x16x32_bf16 v[50:53], v[170:173], v[200:203], v[50:53]
	v_mfma_f32_16x16x32_bf16 v[18:21], v[170:173], v[208:211], v[18:21]
	v_mfma_f32_16x16x32_bf16 v[2:5], v[170:173], v[216:219], v[2:5]
	v_mfma_f32_16x16x32_bf16 v[86:89], v[166:169], v[196:199], v[86:89]
	v_mfma_f32_16x16x32_bf16 v[54:57], v[166:169], v[204:207], v[54:57]
	v_mfma_f32_16x16x32_bf16 v[22:25], v[166:169], v[212:215], v[22:25]
	v_mfma_f32_16x16x32_bf16 v[6:9], v[166:169], v[232:235], v[6:9]
	v_mfma_f32_16x16x32_bf16 v[82:85], v[174:177], v[196:199], v[82:85]
	v_mfma_f32_16x16x32_bf16 v[50:53], v[174:177], v[204:207], v[50:53]
	v_mfma_f32_16x16x32_bf16 v[18:21], v[174:177], v[212:215], v[18:21]
	v_mfma_f32_16x16x32_bf16 v[2:5], v[174:177], v[232:235], v[2:5]
	s_setprio 0
	s_barrier
	s_add_i32 s70, 0, 0x18000
	s_add_i32 s71, 0, 0x1c000
	v_add_u32_e32 v158, s70, v180
	v_add_u32_e32 v174, s71, v180
	ds_read_b128 v[146:149], v158
	ds_read_b128 v[150:153], v158 offset:1024
	ds_read_b128 v[154:157], v158 offset:2048
	ds_read_b128 v[158:161], v158 offset:3072
	ds_read_b128 v[162:165], v174
	ds_read_b128 v[166:169], v174 offset:1024
	ds_read_b128 v[170:173], v174 offset:2048
	ds_read_b128 v[174:177], v174 offset:3072
	s_add_u32 s10, s44, 0xb0000
	s_addc_u32 s11, s45, 0
	s_mov_b32 m0, s54
	v_lshl_add_u64 v[238:239], s[10:11], 0, v[130:131]
	ds_read_b128 v[182:185], v192 offset:32768
	ds_read_b128 v[196:199], v192 offset:33792
	ds_read_b128 v[200:203], v192 offset:34816
	ds_read_b128 v[204:207], v192 offset:35840
	ds_read_b128 v[208:211], v192 offset:36864
	ds_read_b128 v[212:215], v192 offset:37888
	ds_read_b128 v[216:219], v192 offset:38912
	ds_read_b128 v[232:235], v192 offset:39936
	global_load_lds_dwordx4 v[238:239], off
	v_lshl_add_u64 v[238:239], s[10:11], 0, v[134:135]
	s_mov_b32 m0, s55
	s_nop 0
	global_load_lds_dwordx4 v[238:239], off
	s_waitcnt vmcnt(8)
	s_waitcnt lgkmcnt(0)
	s_barrier
	s_setprio 1
	v_mfma_f32_16x16x32_bf16 v[26:29], v[146:149], v[182:185], v[26:29]
	v_mfma_f32_16x16x32_bf16 v[58:61], v[146:149], v[200:203], v[58:61]
	v_mfma_f32_16x16x32_bf16 v[90:93], v[146:149], v[208:211], v[90:93]
	v_mfma_f32_16x16x32_bf16 v[114:117], v[146:149], v[216:219], v[114:117]
	v_mfma_f32_16x16x32_bf16 v[30:33], v[154:157], v[182:185], v[30:33]
	v_mfma_f32_16x16x32_bf16 v[62:65], v[154:157], v[200:203], v[62:65]
	v_mfma_f32_16x16x32_bf16 v[94:97], v[154:157], v[208:211], v[94:97]
	v_mfma_f32_16x16x32_bf16 v[118:121], v[154:157], v[216:219], v[118:121]
	v_mfma_f32_16x16x32_bf16 v[26:29], v[150:153], v[196:199], v[26:29]
	v_mfma_f32_16x16x32_bf16 v[58:61], v[150:153], v[204:207], v[58:61]
	v_mfma_f32_16x16x32_bf16 v[90:93], v[150:153], v[212:215], v[90:93]
	v_mfma_f32_16x16x32_bf16 v[114:117], v[150:153], v[232:235], v[114:117]
	v_mfma_f32_16x16x32_bf16 v[30:33], v[158:161], v[196:199], v[30:33]
	v_mfma_f32_16x16x32_bf16 v[62:65], v[158:161], v[204:207], v[62:65]
	v_mfma_f32_16x16x32_bf16 v[94:97], v[158:161], v[212:215], v[94:97]
	v_mfma_f32_16x16x32_bf16 v[118:121], v[158:161], v[232:235], v[118:121]
	v_mfma_f32_16x16x32_bf16 v[42:45], v[162:165], v[182:185], v[42:45]
	v_mfma_f32_16x16x32_bf16 v[74:77], v[162:165], v[200:203], v[74:77]
	v_mfma_f32_16x16x32_bf16 v[106:109], v[162:165], v[208:211], v[106:109]
	v_mfma_f32_16x16x32_bf16 v[126:129], v[162:165], v[216:219], v[126:129]
	v_mfma_f32_16x16x32_bf16 v[46:49], v[170:173], v[182:185], v[46:49]
	v_mfma_f32_16x16x32_bf16 v[78:81], v[170:173], v[200:203], v[78:81]
	v_mfma_f32_16x16x32_bf16 v[110:113], v[170:173], v[208:211], v[110:113]
	v_mfma_f32_16x16x32_bf16 v[122:125], v[170:173], v[216:219], v[122:125]
	v_mfma_f32_16x16x32_bf16 v[42:45], v[166:169], v[196:199], v[42:45]
	v_mfma_f32_16x16x32_bf16 v[74:77], v[166:169], v[204:207], v[74:77]
	v_mfma_f32_16x16x32_bf16 v[106:109], v[166:169], v[212:215], v[106:109]
	v_mfma_f32_16x16x32_bf16 v[126:129], v[166:169], v[232:235], v[126:129]
	v_mfma_f32_16x16x32_bf16 v[46:49], v[174:177], v[196:199], v[46:49]
	v_mfma_f32_16x16x32_bf16 v[78:81], v[174:177], v[204:207], v[78:81]
	v_mfma_f32_16x16x32_bf16 v[110:113], v[174:177], v[212:215], v[110:113]
	v_mfma_f32_16x16x32_bf16 v[122:125], v[174:177], v[232:235], v[122:125]
	s_setprio 0
	s_barrier
; #define PG8_STAGE(bufoff, gbase, voff) do { _Pragma("unroll") for (int _i = 0; _i < 2; ++_i) \
;         __builtin_amdgcn_global_load_lds((const unsigned*)((const char*)(gbase) + (voff)[_i]), (LAS unsigned*)(lds + (bufoff) + ldsw + _i * 8192), 16, 0, 0); } while (0)
; #define PG8_LDA(dst, b, h) do { _Pragma("unroll") for (int m = 0; m < 4; ++m) _Pragma("unroll") for (int k = 0; k < 2; ++k) dst[m][k] = *(const LAS bf16x8*)(lds + PG8_SA(b, h) + aoff + m * 2048 + k * 1024); } while (0)
; #define PG8_MMA(ai, bj, At, Bt) do { __builtin_amdgcn_s_setprio(1); _Pragma("unroll") for (int m = 0; m < 4; ++m) _Pragma("unroll") for (int n = 0; n < 2; ++n) _Pragma("unroll") for (int k = 0; k < 2; ++k) \
;         acc[ai][bj][m][n] = __builtin_amdgcn_mfma_f32_16x16x32_bf16(Bt[n][k], At[m][k], acc[ai][bj][m][n], 0, 0, 0); __builtin_amdgcn_s_setprio(0); } while (0)
; #define PG8_WAIT_V(n) asm volatile("s_waitcnt vmcnt(" #n ")" ::: "memory")
; #define PG8_WAIT_L(n) asm volatile("s_waitcnt lgkmcnt(" #n ")" ::: "memory")
; #define PG8_BAR __builtin_amdgcn_s_barrier()
; #define PG8_SCHED __builtin_amdgcn_sched_barrier(0)
; template <class Epi>
; __device__ __forceinline__ void gemm_phase(LAS unsigned char* lds, const Gemm g, const StaticOrder& S, const Epi& E) {
;     ...
;             PG8_LDA(At, 1, 1); PG8_STAGE(PG8_SB(1, 0), b3, voffB); PG8_STAGE(PG8_SB(1, 1), b3 + hB, voffB); PG8_STAGE(PG8_SA(1, 0), a3, voffA);
;             PG8_WAIT_V(8); PG8_WAIT_L(0); PG8_BAR; PG8_MMA(1, 0, At, B0); PG8_MMA(1, 1, At, B1); PG8_BAR; PG8_SCHED;
;         }
;         if (wr == 0) PG8_BAR;
	s_add_i32 s10, s70, s47
	v_lshl_add_u64 v[178:179], v[178:179], 0, s[88:89]
	s_mov_b32 m0, s10
	ds_read_b128 v[182:185], v192 offset:49152
	ds_read_b128 v[196:199], v192 offset:50176
	ds_read_b128 v[200:203], v192 offset:51200
	ds_read_b128 v[204:207], v192 offset:52224
	ds_read_b128 v[208:211], v192 offset:53248
	ds_read_b128 v[212:215], v192 offset:54272
	ds_read_b128 v[216:219], v192 offset:55296
	ds_read_b128 v[232:235], v192 offset:56320
	global_load_lds_dwordx4 v[178:179], off
	s_add_i32 m0, s10, 0x2000
	s_add_u32 s10, s42, 0xb0080
	v_lshl_add_u64 v[178:179], v[186:187], 0, s[88:89]
	s_addc_u32 s11, s43, 0
	s_add_i32 s42, s71, s47
	global_load_lds_dwordx4 v[178:179], off
	v_lshl_add_u64 v[178:179], s[10:11], 0, v[132:133]
	s_mov_b32 m0, s42
	s_nop 0
	global_load_lds_dwordx4 v[178:179], off
	v_lshl_add_u64 v[178:179], s[10:11], 0, v[136:137]
	s_add_i32 m0, s42, 0x2000
	s_nop 0
	global_load_lds_dwordx4 v[178:179], off
	v_lshl_add_u64 v[178:179], v[220:221], 0, s[88:89]
	s_mov_b32 m0, s56
	s_nop 0
	global_load_lds_dwordx4 v[178:179], off
	v_lshl_add_u64 v[178:179], v[236:237], 0, s[88:89]
	s_mov_b32 m0, s57
	s_nop 0
	global_load_lds_dwordx4 v[178:179], off
	s_waitcnt vmcnt(8)
	s_waitcnt lgkmcnt(0)
	s_barrier
	s_setprio 1
	v_mfma_f32_16x16x32_bf16 v[102:105], v[146:149], v[182:185], v[102:105]
	v_mfma_f32_16x16x32_bf16 v[70:73], v[146:149], v[200:203], v[70:73]
	v_mfma_f32_16x16x32_bf16 v[38:41], v[146:149], v[208:211], v[38:41]
	v_mfma_f32_16x16x32_bf16 v[14:17], v[146:149], v[216:219], v[14:17]
	v_mfma_f32_16x16x32_bf16 v[98:101], v[154:157], v[182:185], v[98:101]
	v_mfma_f32_16x16x32_bf16 v[66:69], v[154:157], v[200:203], v[66:69]
	v_mfma_f32_16x16x32_bf16 v[34:37], v[154:157], v[208:211], v[34:37]
	v_mfma_f32_16x16x32_bf16 v[10:13], v[154:157], v[216:219], v[10:13]
	v_mfma_f32_16x16x32_bf16 v[102:105], v[150:153], v[196:199], v[102:105]
	v_mfma_f32_16x16x32_bf16 v[70:73], v[150:153], v[204:207], v[70:73]
	v_mfma_f32_16x16x32_bf16 v[38:41], v[150:153], v[212:215], v[38:41]
	v_mfma_f32_16x16x32_bf16 v[14:17], v[150:153], v[232:235], v[14:17]
	v_mfma_f32_16x16x32_bf16 v[98:101], v[158:161], v[196:199], v[98:101]
	v_mfma_f32_16x16x32_bf16 v[66:69], v[158:161], v[204:207], v[66:69]
	v_mfma_f32_16x16x32_bf16 v[34:37], v[158:161], v[212:215], v[34:37]
	v_mfma_f32_16x16x32_bf16 v[10:13], v[158:161], v[232:235], v[10:13]
	v_mfma_f32_16x16x32_bf16 v[86:89], v[162:165], v[182:185], v[86:89]
	v_mfma_f32_16x16x32_bf16 v[54:57], v[162:165], v[200:203], v[54:57]
	v_mfma_f32_16x16x32_bf16 v[22:25], v[162:165], v[208:211], v[22:25]
	v_mfma_f32_16x16x32_bf16 v[6:9], v[162:165], v[216:219], v[6:9]
	v_mfma_f32_16x16x32_bf16 v[82:85], v[170:173], v[182:185], v[82:85]
	v_mfma_f32_16x16x32_bf16 v[50:53], v[170:173], v[200:203], v[50:53]
	v_mfma_f32_16x16x32_bf16 v[18:21], v[170:173], v[208:211], v[18:21]
	v_mfma_f32_16x16x32_bf16 v[2:5], v[170:173], v[216:219], v[2:5]
	v_mfma_f32_16x16x32_bf16 v[86:89], v[166:169], v[196:199], v[86:89]
	v_mfma_f32_16x16x32_bf16 v[54:57], v[166:169], v[204:207], v[54:57]
	v_mfma_f32_16x16x32_bf16 v[22:25], v[166:169], v[212:215], v[22:25]
	v_mfma_f32_16x16x32_bf16 v[6:9], v[166:169], v[232:235], v[6:9]
	v_mfma_f32_16x16x32_bf16 v[82:85], v[174:177], v[196:199], v[82:85]
	v_mfma_f32_16x16x32_bf16 v[50:53], v[174:177], v[204:207], v[50:53]
	v_mfma_f32_16x16x32_bf16 v[18:21], v[174:177], v[212:215], v[18:21]
	v_mfma_f32_16x16x32_bf16 v[2:5], v[174:177], v[232:235], v[2:5]
	s_setprio 0
	s_barrier
	s_add_i32 s67, s67, 2
	s_add_u32 s35, s35, 0x100
	s_addc_u32 s37, s37, 0
	s_cmp_gt_u32 s67, 41
	s_mov_b64 s[10:11], s[8:9]
	s_cbranch_scc0 .LBB0_1632
	s_and_b64 vcc, exec, s[20:21]
	s_cbranch_vccz .LBB0_1635
	s_barrier
